# adds rope epilogue cos/sin software prefetch (two register sets, counted waits, no store drains) and LRU loop store-drain removal
# speedup vs baseline: 1.0046x; 1.0046x over previous
; __device__ __forceinline__ u32x4 pack8f(const f32x4 a, const f32x4 b) { u32x4 w; w.x = cvt_pk_bf16(a[0], a[1]); w.y = cvt_pk_bf16(a[2], a[3]); w.z = cvt_pk_bf16(b[0], b[1]); w.w = cvt_pk_bf16(b[2], b[3]); return w; }
;     __device__ __forceinline__ void operator()(const f32x4 (&acc)[2][2][4][2], const Unit& u, int wr, int wc, int fr, int fq) const {
;         const int sect = u.pn >> 3, hd = u.pn & 7;
;         bf16_t* buf = base + (size_t)sect * ((size_t)QKV_ROWS * 2048);
;         const int j0 = wc * 32 + 8 * fq;
; #pragma unroll
;         for (int ai = 0; ai < 2; ++ai)
; #pragma unroll
;             for (int m = 0; m < 4; ++m) {
;                 const int grow = u.pm * BM + ai * HALF + wr * 64 + m * 16 + fr;
;                 const int pos = NMETA_ + (grow & 4095), srow = (grow >> 12) * TPAD + pos;
;                 const float rr = rs1[grow];
;                 const f32x4 a00 = acc[ai][0][m][0] * rr, a01 = acc[ai][0][m][1] * rr, a10 = acc[ai][1][m][0] * rr, a11 = acc[ai][1][m][1] * rr;
;                 if (sect < 2) {
;                     const int comp = j0 >> 6, i0 = j0 & 63;
;                     const f32x4 c0 = *(const f32x4*)(cosT + pos * 64 + i0), c1 = *(const f32x4*)(cosT + pos * 64 + i0 + 4);
;                     const f32x4 s0 = *(const f32x4*)(sinT + pos * 64 + i0), s1 = *(const f32x4*)(sinT + pos * 64 + i0 + 4);
;                     const f32x4 x1a = a00, x1b = a01, x2a = a10, x2b = a11;
;                     const f32x4 o1a = x1a * c0 - x2a * s0, o1b = x1b * c1 - x2b * s1, o2a = x2a * c0 + x1a * s0, o2b = x2b * c1 + x1b * s1;
;                     const u32x4 w1 = pack8f(o1a, o1b), w2 = pack8f(o2a, o2b);
;                     bf16_t* p = buf + (size_t)srow * 2048 + hd * 256 + comp * 128 + i0;
;                     *(u32x4*)p = w1; *(u32x4*)(p + 64) = w2;
.LBB0_135:
	s_mov_b64 s[86:87], 0x1000
	s_mov_b64 s[88:89], 0x5000
	s_ashr_i32 s35, s44, 3
	s_mul_i32 s3, s35, 0x2100000
	s_mul_hi_i32 s2, s35, 0x2100000
	s_add_u32 s3, s60, s3
	s_addc_u32 s2, s61, s2
	s_cmp_gt_i32 s35, 1
	s_cselect_b64 s[46:47], -1, 0
	s_lshl_b32 s17, s44, 9
	s_and_b32 s17, s17, 0xe00
	s_add_u32 s48, s3, s17
	s_addc_u32 s49, s2, 0
	s_add_u32 s2, s48, s76
	s_addc_u32 s3, s49, 0
	s_lshl_b32 s17, s42, 8
	s_add_i32 s17, s17, s62
	v_or_b32_e32 v154, s17, v158
	v_ashrrev_i32_e32 v155, 31, v154
	v_lshl_add_u64 v[152:153], v[154:155], 2, s[6:7]
	global_load_dword v246, v[152:153], off
	global_load_dword v247, v[152:153], off offset:64
	global_load_dword v248, v[152:153], off offset:128
	global_load_dword v249, v[152:153], off offset:192
	global_load_dword v250, v[152:153], off offset:512
	global_load_dword v251, v[152:153], off offset:576
	global_load_dword v252, v[152:153], off offset:640
	global_load_dword v253, v[152:153], off offset:704
	s_ashr_i32 s44, s17, 12
	s_cmp_lt_i32 s35, 2
	v_and_or_b32 v176, v154, s77, 16
	s_mul_i32 s35, s44, 0x1080
	v_add_u32_e32 v156, s35, v176
	s_mov_b64 s[42:43], -1
	v_lshl_add_u64 v[152:153], s[48:49], 0, v[138:139]
	v_ashrrev_i32_e32 v157, 31, v156
	s_waitcnt vmcnt(0)
	v_mov_b32_e32 v178, v246
	v_pk_mul_f32 v[128:129], v[128:129], v[178:179] op_sel_hi:[1,0]
	v_pk_mul_f32 v[154:155], v[126:127], v[178:179] op_sel_hi:[1,0]
	v_pk_mul_f32 v[124:125], v[124:125], v[178:179] op_sel_hi:[1,0]
	v_pk_mul_f32 v[126:127], v[122:123], v[178:179] op_sel_hi:[1,0]
	v_pk_mul_f32 v[120:121], v[120:121], v[178:179] op_sel_hi:[1,0]
	v_pk_mul_f32 v[122:123], v[118:119], v[178:179] op_sel_hi:[1,0]
	v_pk_mul_f32 v[116:117], v[116:117], v[178:179] op_sel_hi:[1,0]
	v_pk_mul_f32 v[118:119], v[114:115], v[178:179] op_sel_hi:[1,0]
	s_cbranch_scc1 .LBB0_137
	v_lshlrev_b64 v[114:115], 12, v[156:157]
	v_lshl_add_u64 v[114:115], v[152:153], 0, v[114:115]
	v_cvt_pk_bf16_f32 v178, v154, v155
	v_cvt_pk_bf16_f32 v179, v128, v129
	v_cvt_pk_bf16_f32 v180, v126, v127
	v_cvt_pk_bf16_f32 v181, v124, v125
	s_mov_b64 s[42:43], 0
	global_store_dwordx4 v[114:115], v[178:181], off
	s_nop 1
	v_cvt_pk_bf16_f32 v178, v122, v123
	v_cvt_pk_bf16_f32 v179, v120, v121
	v_cvt_pk_bf16_f32 v180, v118, v119
	v_cvt_pk_bf16_f32 v181, v116, v117
	global_store_dwordx4 v[114:115], v[178:181], off offset:256
.LBB0_137:
	v_mov_b32_e32 v149, v139
	s_andn2_b64 vcc, exec, s[42:43]
	v_lshl_add_u64 v[114:115], s[2:3], 0, v[148:149]
	s_cbranch_vccnz .LBB0_139
	v_lshlrev_b32_e32 v184, 8, v176
	v_mov_b32_e32 v185, v139
	v_lshl_add_u64 v[238:239], v[142:143], 0, v[184:185]
	v_lshl_add_u64 v[240:241], v[140:141], 0, v[184:185]
	v_lshl_add_u64 v[180:181], v[142:143], 0, v[184:185]
	global_load_dwordx4 v[176:179], v[180:181], off
	s_nop 0
	global_load_dwordx4 v[180:183], v[180:181], off offset:16
	v_lshl_add_u64 v[188:189], v[140:141], 0, v[184:185]
	global_load_dwordx4 v[184:187], v[188:189], off
	s_nop 0
	global_load_dwordx4 v[188:191], v[188:189], off offset:16
	v_lshl_add_u64 v[238:239], v[238:239], 0, s[86:87]
	v_lshl_add_u64 v[240:241], v[240:241], 0, s[86:87]
	global_load_dwordx4 v[222:225], v[238:239], off
	global_load_dwordx4 v[226:229], v[238:239], off offset:16
	global_load_dwordx4 v[230:233], v[240:241], off
	global_load_dwordx4 v[234:237], v[240:241], off offset:16
	v_lshlrev_b64 v[156:157], 12, v[156:157]
	v_lshl_add_u64 v[156:157], v[114:115], 0, v[156:157]
	s_waitcnt vmcnt(7)
	v_pk_mul_f32 v[192:193], v[120:121], v[178:179]
	v_pk_mul_f32 v[194:195], v[122:123], v[176:177]
	s_waitcnt vmcnt(6)
	v_pk_mul_f32 v[198:199], v[116:117], v[182:183]
	v_pk_mul_f32 v[200:201], v[118:119], v[180:181]
	v_pk_mul_f32 v[178:179], v[128:129], v[178:179]
	v_pk_mul_f32 v[176:177], v[154:155], v[176:177]
	v_pk_mul_f32 v[182:183], v[124:125], v[182:183]
	v_pk_mul_f32 v[180:181], v[126:127], v[180:181]
	s_waitcnt vmcnt(5)
	v_pk_fma_f32 v[128:129], v[128:129], v[186:187], v[192:193] neg_lo:[0,0,1] neg_hi:[0,0,1]
	v_pk_fma_f32 v[154:155], v[154:155], v[184:185], v[194:195] neg_lo:[0,0,1] neg_hi:[0,0,1]
	s_waitcnt vmcnt(4)
	v_pk_fma_f32 v[124:125], v[124:125], v[190:191], v[198:199] neg_lo:[0,0,1] neg_hi:[0,0,1]
	v_pk_fma_f32 v[126:127], v[126:127], v[188:189], v[200:201] neg_lo:[0,0,1] neg_hi:[0,0,1]
	v_pk_fma_f32 v[178:179], v[120:121], v[186:187], v[178:179]
	v_pk_fma_f32 v[120:121], v[122:123], v[184:185], v[176:177]
	v_pk_fma_f32 v[176:177], v[116:117], v[190:191], v[182:183]
	v_pk_fma_f32 v[122:123], v[118:119], v[188:189], v[180:181]
	v_cvt_pk_bf16_f32 v116, v154, v155
	v_cvt_pk_bf16_f32 v117, v128, v129
	v_cvt_pk_bf16_f32 v118, v126, v127
	v_cvt_pk_bf16_f32 v119, v124, v125
	v_cvt_pk_bf16_f32 v120, v120, v121
	v_cvt_pk_bf16_f32 v121, v178, v179
	s_nop 0
	v_cvt_pk_bf16_f32 v122, v122, v123
	v_cvt_pk_bf16_f32 v123, v176, v177
	global_store_dwordx4 v[156:157], v[116:119], off
	global_store_dwordx4 v[156:157], v[120:123], off offset:128
; __device__ __forceinline__ u32x4 pack8f(const f32x4 a, const f32x4 b) { u32x4 w; w.x = cvt_pk_bf16(a[0], a[1]); w.y = cvt_pk_bf16(a[2], a[3]); w.z = cvt_pk_bf16(b[0], b[1]); w.w = cvt_pk_bf16(b[2], b[3]); return w; }
;     __device__ __forceinline__ void operator()(const f32x4 (&acc)[2][2][4][2], const Unit& u, int wr, int wc, int fr, int fq) const {
;     ...
;                 const int grow = u.pm * BM + ai * HALF + wr * 64 + m * 16 + fr;
;                 const int pos = NMETA_ + (grow & 4095), srow = (grow >> 12) * TPAD + pos;
;                 const float rr = rs1[grow];
;                 const f32x4 a00 = acc[ai][0][m][0] * rr, a01 = acc[ai][0][m][1] * rr, a10 = acc[ai][1][m][0] * rr, a11 = acc[ai][1][m][1] * rr;
;                 if (sect < 2) {
;                     const int comp = j0 >> 6, i0 = j0 & 63;
;                     const f32x4 c0 = *(const f32x4*)(cosT + pos * 64 + i0), c1 = *(const f32x4*)(cosT + pos * 64 + i0 + 4);
;                     const f32x4 s0 = *(const f32x4*)(sinT + pos * 64 + i0), s1 = *(const f32x4*)(sinT + pos * 64 + i0 + 4);
;                     const f32x4 x1a = a00, x1b = a01, x2a = a10, x2b = a11;
;                     const f32x4 o1a = x1a * c0 - x2a * s0, o1b = x1b * c1 - x2b * s1, o2a = x2a * c0 + x1a * s0, o2b = x2b * c1 + x1b * s1;
;                     const u32x4 w1 = pack8f(o1a, o1b), w2 = pack8f(o2a, o2b);
;                     bf16_t* p = buf + (size_t)srow * 2048 + hd * 256 + comp * 128 + i0;
;                     *(u32x4*)p = w1; *(u32x4*)(p + 64) = w2;
;                 } else {
; #pragma unroll
;                     for (int bj = 0; bj < 2; ++bj) { const u32x4 w = bj ? pack8f(a10, a11) : pack8f(a00, a01);
;                         bf16_t* p = buf + (size_t)srow * 2048 + hd * 256 + bj * HALF + j0;
;                         *(u32x4*)p = w; }
.LBB0_139:
	s_nop 0
	v_or_b32_e32 v116, s17, v168
	v_ashrrev_i32_e32 v117, 31, v116
	v_lshl_add_u64 v[116:117], v[116:117], 2, s[6:7]
	s_nop 0
	v_bitop3_b32 v116, s17, v174, v168 bitop3:0xc8
	v_add_u32_e32 v118, 16, v116
	v_cndmask_b32_e64 v117, 0, 1, s[46:47]
	v_add_u32_e32 v116, s35, v118
	s_mov_b64 s[42:43], -1
	v_cmp_ne_u32_e64 s[2:3], 1, v117
	s_andn2_b64 vcc, exec, s[46:47]
	v_ashrrev_i32_e32 v117, 31, v116
	v_mov_b32_e32 v120, v247
	v_pk_mul_f32 v[112:113], v[112:113], v[120:121] op_sel_hi:[1,0]
	v_pk_mul_f32 v[110:111], v[110:111], v[120:121] op_sel_hi:[1,0]
	v_pk_mul_f32 v[108:109], v[108:109], v[120:121] op_sel_hi:[1,0]
	v_pk_mul_f32 v[106:107], v[106:107], v[120:121] op_sel_hi:[1,0]
	v_pk_mul_f32 v[104:105], v[104:105], v[120:121] op_sel_hi:[1,0]
	v_pk_mul_f32 v[102:103], v[102:103], v[120:121] op_sel_hi:[1,0]
	v_pk_mul_f32 v[100:101], v[100:101], v[120:121] op_sel_hi:[1,0]
	v_pk_mul_f32 v[98:99], v[98:99], v[120:121] op_sel_hi:[1,0]
	s_cbranch_vccnz .LBB0_141
	v_lshlrev_b64 v[120:121], 12, v[116:117]
	v_lshl_add_u64 v[124:125], v[152:153], 0, v[120:121]
	v_cvt_pk_bf16_f32 v120, v110, v111
	v_cvt_pk_bf16_f32 v121, v112, v113
	v_cvt_pk_bf16_f32 v122, v106, v107
	v_cvt_pk_bf16_f32 v123, v108, v109
	s_mov_b64 s[42:43], 0
	global_store_dwordx4 v[124:125], v[120:123], off
	s_nop 1
	v_cvt_pk_bf16_f32 v120, v102, v103
	v_cvt_pk_bf16_f32 v121, v104, v105
	v_cvt_pk_bf16_f32 v122, v98, v99
	v_cvt_pk_bf16_f32 v123, v100, v101
	global_store_dwordx4 v[124:125], v[120:123], off offset:256
.LBB0_141:
	s_andn2_b64 vcc, exec, s[42:43]
	s_cbranch_vccnz .LBB0_143
	v_lshlrev_b32_e32 v126, 8, v118
	v_mov_b32_e32 v127, v139
	v_lshl_add_u64 v[122:123], v[142:143], 0, v[126:127]
	v_lshl_add_u64 v[238:239], v[238:239], 0, s[86:87]
	v_lshl_add_u64 v[240:241], v[240:241], 0, s[86:87]
	global_load_dwordx4 v[206:209], v[238:239], off
	global_load_dwordx4 v[210:213], v[238:239], off offset:16
	global_load_dwordx4 v[214:217], v[240:241], off
	global_load_dwordx4 v[218:221], v[240:241], off offset:16
	s_nop 0
	v_lshl_add_u64 v[154:155], v[140:141], 0, v[126:127]
	s_nop 0
	v_lshlrev_b64 v[116:117], 12, v[116:117]
	v_lshl_add_u64 v[116:117], v[114:115], 0, v[116:117]
	s_waitcnt vmcnt(9)
	v_pk_mul_f32 v[176:177], v[104:105], v[224:225]
	v_pk_mul_f32 v[178:179], v[102:103], v[222:223]
	s_waitcnt vmcnt(8)
	v_pk_mul_f32 v[180:181], v[100:101], v[228:229]
	v_pk_mul_f32 v[182:183], v[98:99], v[226:227]
	v_pk_mul_f32 v[224:225], v[112:113], v[224:225]
	v_pk_mul_f32 v[222:223], v[110:111], v[222:223]
	v_pk_mul_f32 v[228:229], v[108:109], v[228:229]
	v_pk_mul_f32 v[226:227], v[106:107], v[226:227]
	s_waitcnt vmcnt(7)
	v_pk_fma_f32 v[112:113], v[112:113], v[232:233], v[176:177] neg_lo:[0,0,1] neg_hi:[0,0,1]
	v_pk_fma_f32 v[110:111], v[110:111], v[230:231], v[178:179] neg_lo:[0,0,1] neg_hi:[0,0,1]
	s_waitcnt vmcnt(6)
	v_pk_fma_f32 v[108:109], v[108:109], v[236:237], v[180:181] neg_lo:[0,0,1] neg_hi:[0,0,1]
	v_pk_fma_f32 v[106:107], v[106:107], v[234:235], v[182:183] neg_lo:[0,0,1] neg_hi:[0,0,1]
	v_pk_fma_f32 v[104:105], v[104:105], v[232:233], v[224:225]
	v_pk_fma_f32 v[102:103], v[102:103], v[230:231], v[222:223]
	v_pk_fma_f32 v[222:223], v[100:101], v[236:237], v[228:229]
	v_pk_fma_f32 v[224:225], v[98:99], v[234:235], v[226:227]
	v_cvt_pk_bf16_f32 v98, v110, v111
	v_cvt_pk_bf16_f32 v99, v112, v113
	v_cvt_pk_bf16_f32 v100, v106, v107
	v_cvt_pk_bf16_f32 v101, v108, v109
	v_cvt_pk_bf16_f32 v102, v102, v103
	v_cvt_pk_bf16_f32 v103, v104, v105
	s_nop 0
	v_cvt_pk_bf16_f32 v104, v224, v225
	v_cvt_pk_bf16_f32 v105, v222, v223
	global_store_dwordx4 v[116:117], v[98:101], off
	global_store_dwordx4 v[116:117], v[102:105], off offset:128
.LBB0_143:
	s_nop 0
	v_or_b32_e32 v98, s17, v169
	v_ashrrev_i32_e32 v99, 31, v98
	v_lshl_add_u64 v[100:101], v[98:99], 2, s[6:7]
	s_nop 0
	v_and_or_b32 v100, v98, s78, 16
	v_add_u32_e32 v98, s35, v100
	s_mov_b64 s[42:43], -1
	s_and_b64 vcc, exec, s[2:3]
	v_ashrrev_i32_e32 v99, 31, v98
	v_mov_b32_e32 v102, v248
	v_pk_mul_f32 v[96:97], v[96:97], v[102:103] op_sel_hi:[1,0]
	v_pk_mul_f32 v[94:95], v[94:95], v[102:103] op_sel_hi:[1,0]
	v_pk_mul_f32 v[92:93], v[92:93], v[102:103] op_sel_hi:[1,0]
	v_pk_mul_f32 v[90:91], v[90:91], v[102:103] op_sel_hi:[1,0]
	v_pk_mul_f32 v[88:89], v[88:89], v[102:103] op_sel_hi:[1,0]
	v_pk_mul_f32 v[86:87], v[86:87], v[102:103] op_sel_hi:[1,0]
	v_pk_mul_f32 v[84:85], v[84:85], v[102:103] op_sel_hi:[1,0]
	v_pk_mul_f32 v[82:83], v[82:83], v[102:103] op_sel_hi:[1,0]
	s_cbranch_vccnz .LBB0_145
	v_lshlrev_b64 v[102:103], 12, v[98:99]
	v_lshl_add_u64 v[106:107], v[152:153], 0, v[102:103]
	v_cvt_pk_bf16_f32 v102, v94, v95
	v_cvt_pk_bf16_f32 v103, v96, v97
	v_cvt_pk_bf16_f32 v104, v90, v91
	v_cvt_pk_bf16_f32 v105, v92, v93
	s_mov_b64 s[42:43], 0
	global_store_dwordx4 v[106:107], v[102:105], off
	s_nop 1
	v_cvt_pk_bf16_f32 v102, v86, v87
	v_cvt_pk_bf16_f32 v103, v88, v89
	v_cvt_pk_bf16_f32 v104, v82, v83
	v_cvt_pk_bf16_f32 v105, v84, v85
	global_store_dwordx4 v[106:107], v[102:105], off offset:256
; __device__ __forceinline__ u32x4 pack8f(const f32x4 a, const f32x4 b) { u32x4 w; w.x = cvt_pk_bf16(a[0], a[1]); w.y = cvt_pk_bf16(a[2], a[3]); w.z = cvt_pk_bf16(b[0], b[1]); w.w = cvt_pk_bf16(b[2], b[3]); return w; }
;     __device__ __forceinline__ void operator()(const f32x4 (&acc)[2][2][4][2], const Unit& u, int wr, int wc, int fr, int fq) const {
;     ...
;                 const int grow = u.pm * BM + ai * HALF + wr * 64 + m * 16 + fr;
;                 const int pos = NMETA_ + (grow & 4095), srow = (grow >> 12) * TPAD + pos;
;                 const float rr = rs1[grow];
;                 const f32x4 a00 = acc[ai][0][m][0] * rr, a01 = acc[ai][0][m][1] * rr, a10 = acc[ai][1][m][0] * rr, a11 = acc[ai][1][m][1] * rr;
;                 if (sect < 2) {
;                     const int comp = j0 >> 6, i0 = j0 & 63;
;                     const f32x4 c0 = *(const f32x4*)(cosT + pos * 64 + i0), c1 = *(const f32x4*)(cosT + pos * 64 + i0 + 4);
;                     const f32x4 s0 = *(const f32x4*)(sinT + pos * 64 + i0), s1 = *(const f32x4*)(sinT + pos * 64 + i0 + 4);
;                     const f32x4 x1a = a00, x1b = a01, x2a = a10, x2b = a11;
;                     const f32x4 o1a = x1a * c0 - x2a * s0, o1b = x1b * c1 - x2b * s1, o2a = x2a * c0 + x1a * s0, o2b = x2b * c1 + x1b * s1;
;                     const u32x4 w1 = pack8f(o1a, o1b), w2 = pack8f(o2a, o2b);
;                     bf16_t* p = buf + (size_t)srow * 2048 + hd * 256 + comp * 128 + i0;
;                     *(u32x4*)p = w1; *(u32x4*)(p + 64) = w2;
;                 } else {
; #pragma unroll
;                     for (int bj = 0; bj < 2; ++bj) { const u32x4 w = bj ? pack8f(a10, a11) : pack8f(a00, a01);
;                         bf16_t* p = buf + (size_t)srow * 2048 + hd * 256 + bj * HALF + j0;
;                         *(u32x4*)p = w; }
.LBB0_145:
	s_andn2_b64 vcc, exec, s[42:43]
	s_cbranch_vccnz .LBB0_147
	v_lshlrev_b32_e32 v108, 8, v100
	v_mov_b32_e32 v109, v139
	v_lshl_add_u64 v[104:105], v[142:143], 0, v[108:109]
	v_lshl_add_u64 v[238:239], v[238:239], 0, s[86:87]
	v_lshl_add_u64 v[240:241], v[240:241], 0, s[86:87]
	global_load_dwordx4 v[222:225], v[238:239], off
	global_load_dwordx4 v[226:229], v[238:239], off offset:16
	global_load_dwordx4 v[230:233], v[240:241], off
	global_load_dwordx4 v[234:237], v[240:241], off offset:16
	s_nop 0
	v_lshl_add_u64 v[112:113], v[140:141], 0, v[108:109]
	v_lshlrev_b64 v[98:99], 12, v[98:99]
	v_lshl_add_u64 v[98:99], v[114:115], 0, v[98:99]
	s_waitcnt vmcnt(9)
	v_pk_mul_f32 v[112:113], v[88:89], v[208:209]
	v_pk_mul_f32 v[120:121], v[86:87], v[206:207]
	s_waitcnt vmcnt(8)
	v_pk_mul_f32 v[122:123], v[84:85], v[212:213]
	v_pk_mul_f32 v[124:125], v[82:83], v[210:211]
	v_pk_mul_f32 v[208:209], v[96:97], v[208:209]
	v_pk_mul_f32 v[206:207], v[94:95], v[206:207]
	v_pk_mul_f32 v[212:213], v[92:93], v[212:213]
	v_pk_mul_f32 v[210:211], v[90:91], v[210:211]
	s_waitcnt vmcnt(7)
	v_pk_fma_f32 v[96:97], v[96:97], v[216:217], v[112:113] neg_lo:[0,0,1] neg_hi:[0,0,1]
	v_pk_fma_f32 v[94:95], v[94:95], v[214:215], v[120:121] neg_lo:[0,0,1] neg_hi:[0,0,1]
	s_waitcnt vmcnt(6)
	v_pk_fma_f32 v[92:93], v[92:93], v[220:221], v[122:123] neg_lo:[0,0,1] neg_hi:[0,0,1]
	v_pk_fma_f32 v[90:91], v[90:91], v[218:219], v[124:125] neg_lo:[0,0,1] neg_hi:[0,0,1]
	v_pk_fma_f32 v[88:89], v[88:89], v[216:217], v[208:209]
	v_pk_fma_f32 v[86:87], v[86:87], v[214:215], v[206:207]
	v_pk_fma_f32 v[206:207], v[84:85], v[220:221], v[212:213]
	v_pk_fma_f32 v[208:209], v[82:83], v[218:219], v[210:211]
	v_cvt_pk_bf16_f32 v82, v94, v95
	v_cvt_pk_bf16_f32 v83, v96, v97
	v_cvt_pk_bf16_f32 v84, v90, v91
	v_cvt_pk_bf16_f32 v85, v92, v93
	v_cvt_pk_bf16_f32 v86, v86, v87
	v_cvt_pk_bf16_f32 v87, v88, v89
	s_nop 0
	v_cvt_pk_bf16_f32 v88, v208, v209
	v_cvt_pk_bf16_f32 v89, v206, v207
	global_store_dwordx4 v[98:99], v[82:85], off
	global_store_dwordx4 v[98:99], v[86:89], off offset:128
.LBB0_147:
	s_nop 0
	v_or_b32_e32 v82, s17, v170
	v_ashrrev_i32_e32 v83, 31, v82
	v_lshl_add_u64 v[82:83], v[82:83], 2, s[6:7]
	s_nop 0
	v_bitop3_b32 v82, s17, v175, v170 bitop3:0xc8
	v_add_u32_e32 v84, 16, v82
	v_add_u32_e32 v82, s35, v84
	s_mov_b64 s[42:43], -1
	s_and_b64 vcc, exec, s[2:3]
	v_ashrrev_i32_e32 v83, 31, v82
	v_mov_b32_e32 v86, v249
	v_pk_mul_f32 v[80:81], v[80:81], v[86:87] op_sel_hi:[1,0]
	v_pk_mul_f32 v[78:79], v[78:79], v[86:87] op_sel_hi:[1,0]
	v_pk_mul_f32 v[76:77], v[76:77], v[86:87] op_sel_hi:[1,0]
	v_pk_mul_f32 v[74:75], v[74:75], v[86:87] op_sel_hi:[1,0]
	v_pk_mul_f32 v[72:73], v[72:73], v[86:87] op_sel_hi:[1,0]
	v_pk_mul_f32 v[70:71], v[70:71], v[86:87] op_sel_hi:[1,0]
	v_pk_mul_f32 v[68:69], v[68:69], v[86:87] op_sel_hi:[1,0]
	v_pk_mul_f32 v[66:67], v[66:67], v[86:87] op_sel_hi:[1,0]
	s_cbranch_vccnz .LBB0_149
	v_lshlrev_b64 v[86:87], 12, v[82:83]
	v_lshl_add_u64 v[90:91], v[152:153], 0, v[86:87]
	v_cvt_pk_bf16_f32 v86, v78, v79
	v_cvt_pk_bf16_f32 v87, v80, v81
	v_cvt_pk_bf16_f32 v88, v74, v75
	v_cvt_pk_bf16_f32 v89, v76, v77
	s_mov_b64 s[42:43], 0
	global_store_dwordx4 v[90:91], v[86:89], off
	s_nop 1
	v_cvt_pk_bf16_f32 v86, v70, v71
	v_cvt_pk_bf16_f32 v87, v72, v73
	v_cvt_pk_bf16_f32 v88, v66, v67
	v_cvt_pk_bf16_f32 v89, v68, v69
	global_store_dwordx4 v[90:91], v[86:89], off offset:256
.LBB0_149:
	s_andn2_b64 vcc, exec, s[42:43]
	s_cbranch_vccnz .LBB0_151
	v_lshlrev_b32_e32 v92, 8, v84
	v_mov_b32_e32 v93, v139
	v_lshl_add_u64 v[88:89], v[142:143], 0, v[92:93]
	v_lshl_add_u64 v[238:239], v[238:239], 0, s[88:89]
	v_lshl_add_u64 v[240:241], v[240:241], 0, s[88:89]
	global_load_dwordx4 v[206:209], v[238:239], off
	global_load_dwordx4 v[210:213], v[238:239], off offset:16
	global_load_dwordx4 v[214:217], v[240:241], off
	global_load_dwordx4 v[218:221], v[240:241], off offset:16
	s_nop 0
	v_lshl_add_u64 v[96:97], v[140:141], 0, v[92:93]
	s_nop 0
	v_lshlrev_b64 v[82:83], 12, v[82:83]
	v_lshl_add_u64 v[82:83], v[114:115], 0, v[82:83]
	s_waitcnt vmcnt(9)
	v_pk_mul_f32 v[100:101], v[72:73], v[224:225]
	v_pk_mul_f32 v[102:103], v[70:71], v[222:223]
	s_waitcnt vmcnt(8)
	v_pk_mul_f32 v[104:105], v[68:69], v[228:229]
	v_pk_mul_f32 v[106:107], v[66:67], v[226:227]
	v_pk_mul_f32 v[224:225], v[80:81], v[224:225]
	v_pk_mul_f32 v[222:223], v[78:79], v[222:223]
	v_pk_mul_f32 v[228:229], v[76:77], v[228:229]
	v_pk_mul_f32 v[226:227], v[74:75], v[226:227]
	s_waitcnt vmcnt(7)
	v_pk_fma_f32 v[80:81], v[80:81], v[232:233], v[100:101] neg_lo:[0,0,1] neg_hi:[0,0,1]
	v_pk_fma_f32 v[78:79], v[78:79], v[230:231], v[102:103] neg_lo:[0,0,1] neg_hi:[0,0,1]
	s_waitcnt vmcnt(6)
	v_pk_fma_f32 v[76:77], v[76:77], v[236:237], v[104:105] neg_lo:[0,0,1] neg_hi:[0,0,1]
	v_pk_fma_f32 v[74:75], v[74:75], v[234:235], v[106:107] neg_lo:[0,0,1] neg_hi:[0,0,1]
	v_pk_fma_f32 v[72:73], v[72:73], v[232:233], v[224:225]
	v_pk_fma_f32 v[70:71], v[70:71], v[230:231], v[222:223]
	v_pk_fma_f32 v[222:223], v[68:69], v[236:237], v[228:229]
	v_pk_fma_f32 v[224:225], v[66:67], v[234:235], v[226:227]
	v_cvt_pk_bf16_f32 v66, v78, v79
	v_cvt_pk_bf16_f32 v67, v80, v81
	v_cvt_pk_bf16_f32 v68, v74, v75
	v_cvt_pk_bf16_f32 v69, v76, v77
	v_cvt_pk_bf16_f32 v70, v70, v71
	v_cvt_pk_bf16_f32 v71, v72, v73
	s_nop 0
	v_cvt_pk_bf16_f32 v72, v224, v225
	v_cvt_pk_bf16_f32 v73, v222, v223
	global_store_dwordx4 v[82:83], v[66:69], off
	global_store_dwordx4 v[82:83], v[70:73], off offset:128
; __device__ __forceinline__ u32x4 pack8f(const f32x4 a, const f32x4 b) { u32x4 w; w.x = cvt_pk_bf16(a[0], a[1]); w.y = cvt_pk_bf16(a[2], a[3]); w.z = cvt_pk_bf16(b[0], b[1]); w.w = cvt_pk_bf16(b[2], b[3]); return w; }
;     __device__ __forceinline__ void operator()(const f32x4 (&acc)[2][2][4][2], const Unit& u, int wr, int wc, int fr, int fq) const {
;     ...
;                 const int grow = u.pm * BM + ai * HALF + wr * 64 + m * 16 + fr;
;                 const int pos = NMETA_ + (grow & 4095), srow = (grow >> 12) * TPAD + pos;
;                 const float rr = rs1[grow];
;                 const f32x4 a00 = acc[ai][0][m][0] * rr, a01 = acc[ai][0][m][1] * rr, a10 = acc[ai][1][m][0] * rr, a11 = acc[ai][1][m][1] * rr;
;                 if (sect < 2) {
;                     const int comp = j0 >> 6, i0 = j0 & 63;
;                     const f32x4 c0 = *(const f32x4*)(cosT + pos * 64 + i0), c1 = *(const f32x4*)(cosT + pos * 64 + i0 + 4);
;                     const f32x4 s0 = *(const f32x4*)(sinT + pos * 64 + i0), s1 = *(const f32x4*)(sinT + pos * 64 + i0 + 4);
;                     const f32x4 x1a = a00, x1b = a01, x2a = a10, x2b = a11;
;                     const f32x4 o1a = x1a * c0 - x2a * s0, o1b = x1b * c1 - x2b * s1, o2a = x2a * c0 + x1a * s0, o2b = x2b * c1 + x1b * s1;
;                     const u32x4 w1 = pack8f(o1a, o1b), w2 = pack8f(o2a, o2b);
;                     bf16_t* p = buf + (size_t)srow * 2048 + hd * 256 + comp * 128 + i0;
;                     *(u32x4*)p = w1; *(u32x4*)(p + 64) = w2;
;                 } else {
; #pragma unroll
;                     for (int bj = 0; bj < 2; ++bj) { const u32x4 w = bj ? pack8f(a10, a11) : pack8f(a00, a01);
;                         bf16_t* p = buf + (size_t)srow * 2048 + hd * 256 + bj * HALF + j0;
;                         *(u32x4*)p = w; }
.LBB0_151:
	s_addk_i32 s17, 0x80
	v_or_b32_e32 v66, s17, v158
	v_ashrrev_i32_e32 v67, 31, v66
	v_lshl_add_u64 v[68:69], v[66:67], 2, s[6:7]
	s_nop 0
	s_ashr_i32 s35, s17, 12
	v_and_or_b32 v68, v66, s77, 16
	s_mulk_i32 s35, 0x1080
	v_add_u32_e32 v66, s35, v68
	s_mov_b64 s[42:43], -1
	s_and_b64 vcc, exec, s[2:3]
	v_ashrrev_i32_e32 v67, 31, v66
	v_mov_b32_e32 v70, v250
	v_pk_mul_f32 v[64:65], v[64:65], v[70:71] op_sel_hi:[1,0]
	v_pk_mul_f32 v[62:63], v[62:63], v[70:71] op_sel_hi:[1,0]
	v_pk_mul_f32 v[60:61], v[60:61], v[70:71] op_sel_hi:[1,0]
	v_pk_mul_f32 v[58:59], v[58:59], v[70:71] op_sel_hi:[1,0]
	v_pk_mul_f32 v[56:57], v[56:57], v[70:71] op_sel_hi:[1,0]
	v_pk_mul_f32 v[54:55], v[54:55], v[70:71] op_sel_hi:[1,0]
	v_pk_mul_f32 v[52:53], v[52:53], v[70:71] op_sel_hi:[1,0]
	v_pk_mul_f32 v[50:51], v[50:51], v[70:71] op_sel_hi:[1,0]
	s_cbranch_vccnz .LBB0_153
	v_lshlrev_b64 v[70:71], 12, v[66:67]
	v_lshl_add_u64 v[74:75], v[152:153], 0, v[70:71]
	v_cvt_pk_bf16_f32 v70, v62, v63
	v_cvt_pk_bf16_f32 v71, v64, v65
	v_cvt_pk_bf16_f32 v72, v58, v59
	v_cvt_pk_bf16_f32 v73, v60, v61
	s_mov_b64 s[42:43], 0
	global_store_dwordx4 v[74:75], v[70:73], off
	s_nop 1
	v_cvt_pk_bf16_f32 v70, v54, v55
	v_cvt_pk_bf16_f32 v71, v56, v57
	v_cvt_pk_bf16_f32 v72, v50, v51
	v_cvt_pk_bf16_f32 v73, v52, v53
	global_store_dwordx4 v[74:75], v[70:73], off offset:256
.LBB0_153:
	s_andn2_b64 vcc, exec, s[42:43]
	s_cbranch_vccnz .LBB0_155
	v_lshlrev_b32_e32 v76, 8, v68
	v_mov_b32_e32 v77, v139
	v_lshl_add_u64 v[72:73], v[142:143], 0, v[76:77]
	v_lshl_add_u64 v[238:239], v[238:239], 0, s[86:87]
	v_lshl_add_u64 v[240:241], v[240:241], 0, s[86:87]
	global_load_dwordx4 v[222:225], v[238:239], off
	global_load_dwordx4 v[226:229], v[238:239], off offset:16
	global_load_dwordx4 v[230:233], v[240:241], off
	global_load_dwordx4 v[234:237], v[240:241], off offset:16
	s_nop 0
	v_lshl_add_u64 v[80:81], v[140:141], 0, v[76:77]
	s_nop 0
	v_lshlrev_b64 v[66:67], 12, v[66:67]
	v_lshl_add_u64 v[66:67], v[114:115], 0, v[66:67]
	s_waitcnt vmcnt(9)
	v_pk_mul_f32 v[84:85], v[56:57], v[208:209]
	v_pk_mul_f32 v[86:87], v[54:55], v[206:207]
	s_waitcnt vmcnt(8)
	v_pk_mul_f32 v[88:89], v[52:53], v[212:213]
	v_pk_mul_f32 v[90:91], v[50:51], v[210:211]
	v_pk_mul_f32 v[208:209], v[64:65], v[208:209]
	v_pk_mul_f32 v[206:207], v[62:63], v[206:207]
	v_pk_mul_f32 v[212:213], v[60:61], v[212:213]
	v_pk_mul_f32 v[210:211], v[58:59], v[210:211]
	s_waitcnt vmcnt(7)
	v_pk_fma_f32 v[64:65], v[64:65], v[216:217], v[84:85] neg_lo:[0,0,1] neg_hi:[0,0,1]
	v_pk_fma_f32 v[62:63], v[62:63], v[214:215], v[86:87] neg_lo:[0,0,1] neg_hi:[0,0,1]
	s_waitcnt vmcnt(6)
	v_pk_fma_f32 v[60:61], v[60:61], v[220:221], v[88:89] neg_lo:[0,0,1] neg_hi:[0,0,1]
	v_pk_fma_f32 v[58:59], v[58:59], v[218:219], v[90:91] neg_lo:[0,0,1] neg_hi:[0,0,1]
	v_pk_fma_f32 v[56:57], v[56:57], v[216:217], v[208:209]
	v_pk_fma_f32 v[54:55], v[54:55], v[214:215], v[206:207]
	v_pk_fma_f32 v[206:207], v[52:53], v[220:221], v[212:213]
	v_pk_fma_f32 v[208:209], v[50:51], v[218:219], v[210:211]
	v_cvt_pk_bf16_f32 v50, v62, v63
	v_cvt_pk_bf16_f32 v51, v64, v65
	v_cvt_pk_bf16_f32 v52, v58, v59
	v_cvt_pk_bf16_f32 v53, v60, v61
	v_cvt_pk_bf16_f32 v54, v54, v55
	v_cvt_pk_bf16_f32 v55, v56, v57
	s_nop 0
	v_cvt_pk_bf16_f32 v56, v208, v209
	v_cvt_pk_bf16_f32 v57, v206, v207
	global_store_dwordx4 v[66:67], v[50:53], off
	global_store_dwordx4 v[66:67], v[54:57], off offset:128
.LBB0_155:
	s_nop 0
	v_or_b32_e32 v50, s17, v168
	v_ashrrev_i32_e32 v51, 31, v50
	v_lshl_add_u64 v[50:51], v[50:51], 2, s[6:7]
	s_nop 0
	v_bitop3_b32 v50, s17, v174, v168 bitop3:0xc8
	v_add_u32_e32 v52, 16, v50
	v_add_u32_e32 v50, s35, v52
	s_mov_b64 s[42:43], -1
	s_and_b64 vcc, exec, s[2:3]
	v_ashrrev_i32_e32 v51, 31, v50
	v_mov_b32_e32 v54, v251
	v_pk_mul_f32 v[48:49], v[48:49], v[54:55] op_sel_hi:[1,0]
	v_pk_mul_f32 v[46:47], v[46:47], v[54:55] op_sel_hi:[1,0]
	v_pk_mul_f32 v[44:45], v[44:45], v[54:55] op_sel_hi:[1,0]
	v_pk_mul_f32 v[42:43], v[42:43], v[54:55] op_sel_hi:[1,0]
	v_pk_mul_f32 v[40:41], v[40:41], v[54:55] op_sel_hi:[1,0]
	v_pk_mul_f32 v[38:39], v[38:39], v[54:55] op_sel_hi:[1,0]
	v_pk_mul_f32 v[36:37], v[36:37], v[54:55] op_sel_hi:[1,0]
	v_pk_mul_f32 v[34:35], v[34:35], v[54:55] op_sel_hi:[1,0]
	s_cbranch_vccnz .LBB0_157
	v_lshlrev_b64 v[54:55], 12, v[50:51]
	v_lshl_add_u64 v[58:59], v[152:153], 0, v[54:55]
	v_cvt_pk_bf16_f32 v54, v46, v47
	v_cvt_pk_bf16_f32 v55, v48, v49
	v_cvt_pk_bf16_f32 v56, v42, v43
	v_cvt_pk_bf16_f32 v57, v44, v45
	s_mov_b64 s[42:43], 0
	global_store_dwordx4 v[58:59], v[54:57], off
	s_nop 1
	v_cvt_pk_bf16_f32 v54, v38, v39
	v_cvt_pk_bf16_f32 v55, v40, v41
	v_cvt_pk_bf16_f32 v56, v34, v35
	v_cvt_pk_bf16_f32 v57, v36, v37
	global_store_dwordx4 v[58:59], v[54:57], off offset:256
; __device__ __forceinline__ u32x4 pack8f(const f32x4 a, const f32x4 b) { u32x4 w; w.x = cvt_pk_bf16(a[0], a[1]); w.y = cvt_pk_bf16(a[2], a[3]); w.z = cvt_pk_bf16(b[0], b[1]); w.w = cvt_pk_bf16(b[2], b[3]); return w; }
;     __device__ __forceinline__ void operator()(const f32x4 (&acc)[2][2][4][2], const Unit& u, int wr, int wc, int fr, int fq) const {
;     ...
;                 const int grow = u.pm * BM + ai * HALF + wr * 64 + m * 16 + fr;
;                 const int pos = NMETA_ + (grow & 4095), srow = (grow >> 12) * TPAD + pos;
;                 const float rr = rs1[grow];
;                 const f32x4 a00 = acc[ai][0][m][0] * rr, a01 = acc[ai][0][m][1] * rr, a10 = acc[ai][1][m][0] * rr, a11 = acc[ai][1][m][1] * rr;
;                 if (sect < 2) {
;                     const int comp = j0 >> 6, i0 = j0 & 63;
;                     const f32x4 c0 = *(const f32x4*)(cosT + pos * 64 + i0), c1 = *(const f32x4*)(cosT + pos * 64 + i0 + 4);
;                     const f32x4 s0 = *(const f32x4*)(sinT + pos * 64 + i0), s1 = *(const f32x4*)(sinT + pos * 64 + i0 + 4);
;                     const f32x4 x1a = a00, x1b = a01, x2a = a10, x2b = a11;
;                     const f32x4 o1a = x1a * c0 - x2a * s0, o1b = x1b * c1 - x2b * s1, o2a = x2a * c0 + x1a * s0, o2b = x2b * c1 + x1b * s1;
;                     const u32x4 w1 = pack8f(o1a, o1b), w2 = pack8f(o2a, o2b);
;                     bf16_t* p = buf + (size_t)srow * 2048 + hd * 256 + comp * 128 + i0;
;                     *(u32x4*)p = w1; *(u32x4*)(p + 64) = w2;
;                 } else {
; #pragma unroll
;                     for (int bj = 0; bj < 2; ++bj) { const u32x4 w = bj ? pack8f(a10, a11) : pack8f(a00, a01);
;                         bf16_t* p = buf + (size_t)srow * 2048 + hd * 256 + bj * HALF + j0;
;                         *(u32x4*)p = w; }
.LBB0_157:
	s_andn2_b64 vcc, exec, s[42:43]
	s_cbranch_vccnz .LBB0_159
	v_lshlrev_b32_e32 v60, 8, v52
	v_mov_b32_e32 v61, v139
	v_lshl_add_u64 v[56:57], v[142:143], 0, v[60:61]
	v_lshl_add_u64 v[238:239], v[238:239], 0, s[86:87]
	v_lshl_add_u64 v[240:241], v[240:241], 0, s[86:87]
	global_load_dwordx4 v[206:209], v[238:239], off
	global_load_dwordx4 v[210:213], v[238:239], off offset:16
	global_load_dwordx4 v[214:217], v[240:241], off
	global_load_dwordx4 v[218:221], v[240:241], off offset:16
	s_nop 0
	v_lshl_add_u64 v[64:65], v[140:141], 0, v[60:61]
	s_nop 0
	v_lshlrev_b64 v[50:51], 12, v[50:51]
	v_lshl_add_u64 v[50:51], v[114:115], 0, v[50:51]
	s_waitcnt vmcnt(9)
	v_pk_mul_f32 v[68:69], v[40:41], v[224:225]
	v_pk_mul_f32 v[70:71], v[38:39], v[222:223]
	s_waitcnt vmcnt(8)
	v_pk_mul_f32 v[72:73], v[36:37], v[228:229]
	v_pk_mul_f32 v[74:75], v[34:35], v[226:227]
	v_pk_mul_f32 v[224:225], v[48:49], v[224:225]
	v_pk_mul_f32 v[222:223], v[46:47], v[222:223]
	v_pk_mul_f32 v[228:229], v[44:45], v[228:229]
	v_pk_mul_f32 v[226:227], v[42:43], v[226:227]
	s_waitcnt vmcnt(7)
	v_pk_fma_f32 v[48:49], v[48:49], v[232:233], v[68:69] neg_lo:[0,0,1] neg_hi:[0,0,1]
	v_pk_fma_f32 v[46:47], v[46:47], v[230:231], v[70:71] neg_lo:[0,0,1] neg_hi:[0,0,1]
	s_waitcnt vmcnt(6)
	v_pk_fma_f32 v[44:45], v[44:45], v[236:237], v[72:73] neg_lo:[0,0,1] neg_hi:[0,0,1]
	v_pk_fma_f32 v[42:43], v[42:43], v[234:235], v[74:75] neg_lo:[0,0,1] neg_hi:[0,0,1]
	v_pk_fma_f32 v[40:41], v[40:41], v[232:233], v[224:225]
	v_pk_fma_f32 v[38:39], v[38:39], v[230:231], v[222:223]
	v_pk_fma_f32 v[222:223], v[36:37], v[236:237], v[228:229]
	v_pk_fma_f32 v[224:225], v[34:35], v[234:235], v[226:227]
	v_cvt_pk_bf16_f32 v34, v46, v47
	v_cvt_pk_bf16_f32 v35, v48, v49
	v_cvt_pk_bf16_f32 v36, v42, v43
	v_cvt_pk_bf16_f32 v37, v44, v45
	v_cvt_pk_bf16_f32 v38, v38, v39
	v_cvt_pk_bf16_f32 v39, v40, v41
	s_nop 0
	v_cvt_pk_bf16_f32 v40, v224, v225
	v_cvt_pk_bf16_f32 v41, v222, v223
	global_store_dwordx4 v[50:51], v[34:37], off
	global_store_dwordx4 v[50:51], v[38:41], off offset:128
.LBB0_159:
	s_nop 0
	v_or_b32_e32 v34, s17, v169
	v_ashrrev_i32_e32 v35, 31, v34
	v_lshl_add_u64 v[36:37], v[34:35], 2, s[6:7]
	s_nop 0
	v_and_or_b32 v36, v34, s78, 16
	v_add_u32_e32 v34, s35, v36
	s_mov_b64 s[42:43], -1
	s_and_b64 vcc, exec, s[2:3]
	v_ashrrev_i32_e32 v35, 31, v34
	v_mov_b32_e32 v38, v252
	v_pk_mul_f32 v[32:33], v[32:33], v[38:39] op_sel_hi:[1,0]
	v_pk_mul_f32 v[30:31], v[30:31], v[38:39] op_sel_hi:[1,0]
	v_pk_mul_f32 v[28:29], v[28:29], v[38:39] op_sel_hi:[1,0]
	v_pk_mul_f32 v[26:27], v[26:27], v[38:39] op_sel_hi:[1,0]
	v_pk_mul_f32 v[24:25], v[24:25], v[38:39] op_sel_hi:[1,0]
	v_pk_mul_f32 v[22:23], v[22:23], v[38:39] op_sel_hi:[1,0]
	v_pk_mul_f32 v[20:21], v[20:21], v[38:39] op_sel_hi:[1,0]
	v_pk_mul_f32 v[18:19], v[18:19], v[38:39] op_sel_hi:[1,0]
	s_cbranch_vccnz .LBB0_161
	v_lshlrev_b64 v[38:39], 12, v[34:35]
	v_lshl_add_u64 v[42:43], v[152:153], 0, v[38:39]
	v_cvt_pk_bf16_f32 v38, v30, v31
	v_cvt_pk_bf16_f32 v39, v32, v33
	v_cvt_pk_bf16_f32 v40, v26, v27
	v_cvt_pk_bf16_f32 v41, v28, v29
	s_mov_b64 s[42:43], 0
	global_store_dwordx4 v[42:43], v[38:41], off
	s_nop 1
	v_cvt_pk_bf16_f32 v38, v22, v23
	v_cvt_pk_bf16_f32 v39, v24, v25
	v_cvt_pk_bf16_f32 v40, v18, v19
	v_cvt_pk_bf16_f32 v41, v20, v21
	global_store_dwordx4 v[42:43], v[38:41], off offset:256
.LBB0_161:
	s_andn2_b64 vcc, exec, s[42:43]
	s_cbranch_vccnz .LBB0_163
	v_lshlrev_b32_e32 v44, 8, v36
	v_mov_b32_e32 v45, v139
	v_lshl_add_u64 v[40:41], v[142:143], 0, v[44:45]
	v_lshl_add_u64 v[238:239], v[238:239], 0, s[86:87]
	v_lshl_add_u64 v[240:241], v[240:241], 0, s[86:87]
	global_load_dwordx4 v[222:225], v[238:239], off
	global_load_dwordx4 v[226:229], v[238:239], off offset:16
	global_load_dwordx4 v[230:233], v[240:241], off
	global_load_dwordx4 v[234:237], v[240:241], off offset:16
	s_nop 0
	v_lshl_add_u64 v[48:49], v[140:141], 0, v[44:45]
	s_nop 0
	v_lshlrev_b64 v[34:35], 12, v[34:35]
	v_lshl_add_u64 v[34:35], v[114:115], 0, v[34:35]
	s_waitcnt vmcnt(9)
	v_pk_mul_f32 v[52:53], v[24:25], v[208:209]
	v_pk_mul_f32 v[54:55], v[22:23], v[206:207]
	s_waitcnt vmcnt(8)
	v_pk_mul_f32 v[56:57], v[20:21], v[212:213]
	v_pk_mul_f32 v[58:59], v[18:19], v[210:211]
	v_pk_mul_f32 v[208:209], v[32:33], v[208:209]
	v_pk_mul_f32 v[206:207], v[30:31], v[206:207]
	v_pk_mul_f32 v[212:213], v[28:29], v[212:213]
	v_pk_mul_f32 v[210:211], v[26:27], v[210:211]
	s_waitcnt vmcnt(7)
	v_pk_fma_f32 v[32:33], v[32:33], v[216:217], v[52:53] neg_lo:[0,0,1] neg_hi:[0,0,1]
	v_pk_fma_f32 v[30:31], v[30:31], v[214:215], v[54:55] neg_lo:[0,0,1] neg_hi:[0,0,1]
	s_waitcnt vmcnt(6)
	v_pk_fma_f32 v[28:29], v[28:29], v[220:221], v[56:57] neg_lo:[0,0,1] neg_hi:[0,0,1]
	v_pk_fma_f32 v[26:27], v[26:27], v[218:219], v[58:59] neg_lo:[0,0,1] neg_hi:[0,0,1]
	v_pk_fma_f32 v[24:25], v[24:25], v[216:217], v[208:209]
	v_pk_fma_f32 v[22:23], v[22:23], v[214:215], v[206:207]
	v_pk_fma_f32 v[206:207], v[20:21], v[220:221], v[212:213]
	v_pk_fma_f32 v[208:209], v[18:19], v[218:219], v[210:211]
	v_cvt_pk_bf16_f32 v18, v30, v31
	v_cvt_pk_bf16_f32 v19, v32, v33
	v_cvt_pk_bf16_f32 v20, v26, v27
	v_cvt_pk_bf16_f32 v21, v28, v29
	v_cvt_pk_bf16_f32 v22, v22, v23
	v_cvt_pk_bf16_f32 v23, v24, v25
	s_nop 0
	v_cvt_pk_bf16_f32 v24, v208, v209
	v_cvt_pk_bf16_f32 v25, v206, v207
	global_store_dwordx4 v[34:35], v[18:21], off
	global_store_dwordx4 v[34:35], v[22:25], off offset:128
.LBB0_163:
	s_nop 0
	v_or_b32_e32 v18, s17, v170
	v_ashrrev_i32_e32 v19, 31, v18
	v_lshl_add_u64 v[18:19], v[18:19], 2, s[6:7]
	s_nop 0
	v_bitop3_b32 v18, s17, v175, v170 bitop3:0xc8
	v_add_u32_e32 v20, 16, v18
	v_add_u32_e32 v18, s35, v20
	s_mov_b64 s[42:43], -1
	s_and_b64 vcc, exec, s[2:3]
	v_ashrrev_i32_e32 v19, 31, v18
	v_mov_b32_e32 v22, v253
	v_pk_mul_f32 v[16:17], v[16:17], v[22:23] op_sel_hi:[1,0]
	v_pk_mul_f32 v[14:15], v[14:15], v[22:23] op_sel_hi:[1,0]
	v_pk_mul_f32 v[12:13], v[12:13], v[22:23] op_sel_hi:[1,0]
	v_pk_mul_f32 v[10:11], v[10:11], v[22:23] op_sel_hi:[1,0]
	v_pk_mul_f32 v[8:9], v[8:9], v[22:23] op_sel_hi:[1,0]
	v_pk_mul_f32 v[6:7], v[6:7], v[22:23] op_sel_hi:[1,0]
	v_pk_mul_f32 v[4:5], v[4:5], v[22:23] op_sel_hi:[1,0]
	v_pk_mul_f32 v[2:3], v[2:3], v[22:23] op_sel_hi:[1,0]
	s_cbranch_vccz .LBB0_166
	s_andn2_b64 vcc, exec, s[42:43]
	s_cbranch_vccz .LBB0_167

; __device__ __forceinline__ u32x4 pack8f(const f32x4 a, const f32x4 b) { u32x4 w; w.x = cvt_pk_bf16(a[0], a[1]); w.y = cvt_pk_bf16(a[2], a[3]); w.z = cvt_pk_bf16(b[0], b[1]); w.w = cvt_pk_bf16(b[2], b[3]); return w; }
;     __device__ __forceinline__ void operator()(const f32x4 (&acc)[2][2][4][2], const Unit& u, int wr, int wc, int fr, int fq) const {
;     ...
;                     const int comp = j0 >> 6, i0 = j0 & 63;
;                     const f32x4 c0 = *(const f32x4*)(cosT + pos * 64 + i0), c1 = *(const f32x4*)(cosT + pos * 64 + i0 + 4);
;                     const f32x4 s0 = *(const f32x4*)(sinT + pos * 64 + i0), s1 = *(const f32x4*)(sinT + pos * 64 + i0 + 4);
;                     const f32x4 x1a = a00, x1b = a01, x2a = a10, x2b = a11;
;                     const f32x4 o1a = x1a * c0 - x2a * s0, o1b = x1b * c1 - x2b * s1, o2a = x2a * c0 + x1a * s0, o2b = x2b * c1 + x1b * s1;
;                     const u32x4 w1 = pack8f(o1a, o1b), w2 = pack8f(o2a, o2b);
;                     bf16_t* p = buf + (size_t)srow * 2048 + hd * 256 + comp * 128 + i0;
;                     *(u32x4*)p = w1; *(u32x4*)(p + 64) = w2;
.LBB0_167:
	v_lshlrev_b32_e32 v28, 8, v20
	v_mov_b32_e32 v29, v139
	v_lshl_add_u64 v[24:25], v[142:143], 0, v[28:29]
	s_nop 0
	s_nop 0
	v_lshl_add_u64 v[32:33], v[140:141], 0, v[28:29]
	s_nop 0
	v_lshlrev_b64 v[18:19], 12, v[18:19]
	v_lshl_add_u64 v[18:19], v[114:115], 0, v[18:19]
	s_waitcnt vmcnt(5)
	v_pk_mul_f32 v[36:37], v[8:9], v[224:225]
	v_pk_mul_f32 v[38:39], v[6:7], v[222:223]
	s_waitcnt vmcnt(4)
	v_pk_mul_f32 v[40:41], v[4:5], v[228:229]
	v_pk_mul_f32 v[42:43], v[2:3], v[226:227]
	v_pk_mul_f32 v[224:225], v[16:17], v[224:225]
	v_pk_mul_f32 v[222:223], v[14:15], v[222:223]
	v_pk_mul_f32 v[228:229], v[12:13], v[228:229]
	v_pk_mul_f32 v[226:227], v[10:11], v[226:227]
	s_waitcnt vmcnt(3)
	v_pk_fma_f32 v[16:17], v[16:17], v[232:233], v[36:37] neg_lo:[0,0,1] neg_hi:[0,0,1]
	v_pk_fma_f32 v[14:15], v[14:15], v[230:231], v[38:39] neg_lo:[0,0,1] neg_hi:[0,0,1]
	s_waitcnt vmcnt(2)
	v_pk_fma_f32 v[12:13], v[12:13], v[236:237], v[40:41] neg_lo:[0,0,1] neg_hi:[0,0,1]
	v_pk_fma_f32 v[10:11], v[10:11], v[234:235], v[42:43] neg_lo:[0,0,1] neg_hi:[0,0,1]
	v_pk_fma_f32 v[8:9], v[8:9], v[232:233], v[224:225]
	v_pk_fma_f32 v[6:7], v[6:7], v[230:231], v[222:223]
	v_pk_fma_f32 v[222:223], v[4:5], v[236:237], v[228:229]
	v_pk_fma_f32 v[224:225], v[2:3], v[234:235], v[226:227]
	v_cvt_pk_bf16_f32 v2, v14, v15
	v_cvt_pk_bf16_f32 v3, v16, v17
	v_cvt_pk_bf16_f32 v4, v10, v11
	v_cvt_pk_bf16_f32 v5, v12, v13
	v_cvt_pk_bf16_f32 v6, v6, v7
	v_cvt_pk_bf16_f32 v7, v8, v9
	s_nop 0
	v_cvt_pk_bf16_f32 v8, v224, v225
	v_cvt_pk_bf16_f32 v9, v222, v223
	global_store_dwordx4 v[18:19], v[2:5], off
	global_store_dwordx4 v[18:19], v[6:9], off offset:128
	s_andn2_b64 vcc, exec, s[36:37]
	s_mov_b64 s[2:3], -1
	s_cbranch_vccnz .LBB0_127

; __device__ __forceinline__ u32x4 pack8f(const f32x4 a, const f32x4 b) { u32x4 w; w.x = cvt_pk_bf16(a[0], a[1]); w.y = cvt_pk_bf16(a[2], a[3]); w.z = cvt_pk_bf16(b[0], b[1]); w.w = cvt_pk_bf16(b[2], b[3]); return w; }
;     __device__ __forceinline__ void operator()(const f32x4 (&acc)[2][2][4][2], const Unit& u, int wr, int wc, int fr, int fq) const {
;         const int sect = u.pn >> 3, hd = u.pn & 7;
;         bf16_t* buf = base + (size_t)sect * ((size_t)QKV_ROWS * 2048);
;         const int j0 = wc * 32 + 8 * fq;
; #pragma unroll
;         for (int ai = 0; ai < 2; ++ai)
; #pragma unroll
;             for (int m = 0; m < 4; ++m) {
;                 const int grow = u.pm * BM + ai * HALF + wr * 64 + m * 16 + fr;
;                 const int pos = NMETA_ + (grow & 4095), srow = (grow >> 12) * TPAD + pos;
;                 const float rr = rs1[grow];
;                 const f32x4 a00 = acc[ai][0][m][0] * rr, a01 = acc[ai][0][m][1] * rr, a10 = acc[ai][1][m][0] * rr, a11 = acc[ai][1][m][1] * rr;
;                 if (sect < 2) {
;                     const int comp = j0 >> 6, i0 = j0 & 63;
;                     const f32x4 c0 = *(const f32x4*)(cosT + pos * 64 + i0), c1 = *(const f32x4*)(cosT + pos * 64 + i0 + 4);
;                     const f32x4 s0 = *(const f32x4*)(sinT + pos * 64 + i0), s1 = *(const f32x4*)(sinT + pos * 64 + i0 + 4);
;                     const f32x4 x1a = a00, x1b = a01, x2a = a10, x2b = a11;
;                     const f32x4 o1a = x1a * c0 - x2a * s0, o1b = x1b * c1 - x2b * s1, o2a = x2a * c0 + x1a * s0, o2b = x2b * c1 + x1b * s1;
;                     const u32x4 w1 = pack8f(o1a, o1b), w2 = pack8f(o2a, o2b);
;                     bf16_t* p = buf + (size_t)srow * 2048 + hd * 256 + comp * 128 + i0;
;                     *(u32x4*)p = w1; *(u32x4*)(p + 64) = w2;
.LBB0_220:
	s_mov_b64 s[86:87], 0x1000
	s_mov_b64 s[88:89], 0x5000
	s_ashr_i32 s35, s42, 3
	s_mul_i32 s17, s35, 0x2100000
	s_mul_hi_i32 s3, s35, 0x2100000
	s_add_u32 s17, s61, s17
	s_addc_u32 s3, s62, s3
	s_cmp_gt_i32 s35, 1
	s_cselect_b64 s[44:45], -1, 0
	s_lshl_b32 s42, s42, 9
	s_and_b32 s42, s42, 0xe00
	s_add_u32 s46, s17, s42
	s_addc_u32 s47, s3, 0
	s_add_u32 s42, s46, s75
	s_addc_u32 s43, s47, 0
	s_lshl_b32 s17, s2, 8
	s_add_i32 s17, s17, s63
	v_or_b32_e32 v154, s17, v158
	v_ashrrev_i32_e32 v155, 31, v154
	v_lshl_add_u64 v[152:153], v[154:155], 2, s[6:7]
	global_load_dword v246, v[152:153], off
	global_load_dword v247, v[152:153], off offset:64
	global_load_dword v248, v[152:153], off offset:128
	global_load_dword v249, v[152:153], off offset:192
	global_load_dword v250, v[152:153], off offset:512
	global_load_dword v251, v[152:153], off offset:576
	global_load_dword v252, v[152:153], off offset:640
	global_load_dword v253, v[152:153], off offset:704
	v_lshl_add_u64 v[152:153], s[46:47], 0, v[138:139]
	s_ashr_i32 s46, s17, 12
	s_cmp_lt_i32 s35, 2
	v_and_or_b32 v168, v154, s76, 16
	s_mul_i32 s35, s46, 0x1080
	v_add_u32_e32 v156, s35, v168
	s_mov_b64 s[2:3], -1
	v_ashrrev_i32_e32 v157, 31, v156
	s_waitcnt vmcnt(0)
	v_mov_b32_e32 v170, v246
	v_pk_mul_f32 v[128:129], v[128:129], v[170:171] op_sel_hi:[1,0]
	v_pk_mul_f32 v[154:155], v[126:127], v[170:171] op_sel_hi:[1,0]
	v_pk_mul_f32 v[124:125], v[124:125], v[170:171] op_sel_hi:[1,0]
	v_pk_mul_f32 v[126:127], v[122:123], v[170:171] op_sel_hi:[1,0]
	v_pk_mul_f32 v[120:121], v[120:121], v[170:171] op_sel_hi:[1,0]
	v_pk_mul_f32 v[122:123], v[118:119], v[170:171] op_sel_hi:[1,0]
	v_pk_mul_f32 v[116:117], v[116:117], v[170:171] op_sel_hi:[1,0]
	v_pk_mul_f32 v[118:119], v[114:115], v[170:171] op_sel_hi:[1,0]
	s_cbranch_scc1 .LBB0_222
	v_lshlrev_b64 v[114:115], 12, v[156:157]
	v_lshl_add_u64 v[114:115], v[152:153], 0, v[114:115]
	v_cvt_pk_bf16_f32 v170, v154, v155
	v_cvt_pk_bf16_f32 v171, v128, v129
	v_cvt_pk_bf16_f32 v172, v126, v127
	v_cvt_pk_bf16_f32 v173, v124, v125
	s_mov_b64 s[2:3], 0
	global_store_dwordx4 v[114:115], v[170:173], off
	s_nop 1
	v_cvt_pk_bf16_f32 v170, v122, v123
	v_cvt_pk_bf16_f32 v171, v120, v121
	v_cvt_pk_bf16_f32 v172, v118, v119
	v_cvt_pk_bf16_f32 v173, v116, v117
	global_store_dwordx4 v[114:115], v[170:173], off offset:256
.LBB0_222:
	v_mov_b32_e32 v149, v139
	s_andn2_b64 vcc, exec, s[2:3]
	v_lshl_add_u64 v[114:115], s[42:43], 0, v[148:149]
	s_cbranch_vccnz .LBB0_224
	v_lshlrev_b32_e32 v176, 8, v168
	v_mov_b32_e32 v177, v139
	v_lshl_add_u64 v[238:239], v[142:143], 0, v[176:177]
	v_lshl_add_u64 v[240:241], v[140:141], 0, v[176:177]
	v_lshl_add_u64 v[172:173], v[142:143], 0, v[176:177]
	global_load_dwordx4 v[168:171], v[172:173], off
	s_nop 0
	global_load_dwordx4 v[172:175], v[172:173], off offset:16
	v_lshl_add_u64 v[180:181], v[140:141], 0, v[176:177]
	global_load_dwordx4 v[176:179], v[180:181], off
	s_nop 0
	global_load_dwordx4 v[180:183], v[180:181], off offset:16
	v_lshl_add_u64 v[238:239], v[238:239], 0, s[86:87]
	v_lshl_add_u64 v[240:241], v[240:241], 0, s[86:87]
	global_load_dwordx4 v[222:225], v[238:239], off
	global_load_dwordx4 v[226:229], v[238:239], off offset:16
	global_load_dwordx4 v[230:233], v[240:241], off
	global_load_dwordx4 v[234:237], v[240:241], off offset:16
	v_lshlrev_b64 v[156:157], 12, v[156:157]
	v_lshl_add_u64 v[156:157], v[114:115], 0, v[156:157]
	s_waitcnt vmcnt(7)
	v_pk_mul_f32 v[184:185], v[120:121], v[170:171]
	v_pk_mul_f32 v[186:187], v[122:123], v[168:169]
	s_waitcnt vmcnt(6)
	v_pk_mul_f32 v[188:189], v[116:117], v[174:175]
	v_pk_mul_f32 v[190:191], v[118:119], v[172:173]
	v_pk_mul_f32 v[170:171], v[128:129], v[170:171]
	v_pk_mul_f32 v[168:169], v[154:155], v[168:169]
	v_pk_mul_f32 v[174:175], v[124:125], v[174:175]
	v_pk_mul_f32 v[172:173], v[126:127], v[172:173]
	s_waitcnt vmcnt(5)
	v_pk_fma_f32 v[128:129], v[128:129], v[178:179], v[184:185] neg_lo:[0,0,1] neg_hi:[0,0,1]
	v_pk_fma_f32 v[154:155], v[154:155], v[176:177], v[186:187] neg_lo:[0,0,1] neg_hi:[0,0,1]
	s_waitcnt vmcnt(4)
	v_pk_fma_f32 v[124:125], v[124:125], v[182:183], v[188:189] neg_lo:[0,0,1] neg_hi:[0,0,1]
	v_pk_fma_f32 v[126:127], v[126:127], v[180:181], v[190:191] neg_lo:[0,0,1] neg_hi:[0,0,1]
	v_pk_fma_f32 v[170:171], v[120:121], v[178:179], v[170:171]
	v_pk_fma_f32 v[120:121], v[122:123], v[176:177], v[168:169]
	v_pk_fma_f32 v[168:169], v[116:117], v[182:183], v[174:175]
	v_pk_fma_f32 v[122:123], v[118:119], v[180:181], v[172:173]
	v_cvt_pk_bf16_f32 v116, v154, v155
	v_cvt_pk_bf16_f32 v117, v128, v129
	v_cvt_pk_bf16_f32 v118, v126, v127
	v_cvt_pk_bf16_f32 v119, v124, v125
	v_cvt_pk_bf16_f32 v120, v120, v121
	v_cvt_pk_bf16_f32 v121, v170, v171
	s_nop 0
	v_cvt_pk_bf16_f32 v122, v122, v123
	v_cvt_pk_bf16_f32 v123, v168, v169
	global_store_dwordx4 v[156:157], v[116:119], off
	global_store_dwordx4 v[156:157], v[120:123], off offset:128
; __device__ __forceinline__ u32x4 pack8f(const f32x4 a, const f32x4 b) { u32x4 w; w.x = cvt_pk_bf16(a[0], a[1]); w.y = cvt_pk_bf16(a[2], a[3]); w.z = cvt_pk_bf16(b[0], b[1]); w.w = cvt_pk_bf16(b[2], b[3]); return w; }
;     __device__ __forceinline__ void operator()(const f32x4 (&acc)[2][2][4][2], const Unit& u, int wr, int wc, int fr, int fq) const {
;     ...
;                 const int grow = u.pm * BM + ai * HALF + wr * 64 + m * 16 + fr;
;                 const int pos = NMETA_ + (grow & 4095), srow = (grow >> 12) * TPAD + pos;
;                 const float rr = rs1[grow];
;                 const f32x4 a00 = acc[ai][0][m][0] * rr, a01 = acc[ai][0][m][1] * rr, a10 = acc[ai][1][m][0] * rr, a11 = acc[ai][1][m][1] * rr;
;                 if (sect < 2) {
;                     const int comp = j0 >> 6, i0 = j0 & 63;
;                     const f32x4 c0 = *(const f32x4*)(cosT + pos * 64 + i0), c1 = *(const f32x4*)(cosT + pos * 64 + i0 + 4);
;                     const f32x4 s0 = *(const f32x4*)(sinT + pos * 64 + i0), s1 = *(const f32x4*)(sinT + pos * 64 + i0 + 4);
;                     const f32x4 x1a = a00, x1b = a01, x2a = a10, x2b = a11;
;                     const f32x4 o1a = x1a * c0 - x2a * s0, o1b = x1b * c1 - x2b * s1, o2a = x2a * c0 + x1a * s0, o2b = x2b * c1 + x1b * s1;
;                     const u32x4 w1 = pack8f(o1a, o1b), w2 = pack8f(o2a, o2b);
;                     bf16_t* p = buf + (size_t)srow * 2048 + hd * 256 + comp * 128 + i0;
;                     *(u32x4*)p = w1; *(u32x4*)(p + 64) = w2;
;                 } else {
; #pragma unroll
;                     for (int bj = 0; bj < 2; ++bj) { const u32x4 w = bj ? pack8f(a10, a11) : pack8f(a00, a01);
;                         bf16_t* p = buf + (size_t)srow * 2048 + hd * 256 + bj * HALF + j0;
;                         *(u32x4*)p = w; }
.LBB0_224:
	s_nop 0
	v_or_b32_e32 v116, s17, v163
	v_ashrrev_i32_e32 v117, 31, v116
	v_lshl_add_u64 v[116:117], v[116:117], 2, s[6:7]
	s_nop 0
	v_bitop3_b32 v116, s17, v162, v163 bitop3:0xc8
	v_add_u32_e32 v118, 16, v116
	v_cndmask_b32_e64 v117, 0, 1, s[44:45]
	v_add_u32_e32 v116, s35, v118
	s_mov_b64 s[42:43], -1
	v_cmp_ne_u32_e64 s[2:3], 1, v117
	s_andn2_b64 vcc, exec, s[44:45]
	v_ashrrev_i32_e32 v117, 31, v116
	v_mov_b32_e32 v120, v247
	v_pk_mul_f32 v[112:113], v[112:113], v[120:121] op_sel_hi:[1,0]
	v_pk_mul_f32 v[110:111], v[110:111], v[120:121] op_sel_hi:[1,0]
	v_pk_mul_f32 v[108:109], v[108:109], v[120:121] op_sel_hi:[1,0]
	v_pk_mul_f32 v[106:107], v[106:107], v[120:121] op_sel_hi:[1,0]
	v_pk_mul_f32 v[104:105], v[104:105], v[120:121] op_sel_hi:[1,0]
	v_pk_mul_f32 v[102:103], v[102:103], v[120:121] op_sel_hi:[1,0]
	v_pk_mul_f32 v[100:101], v[100:101], v[120:121] op_sel_hi:[1,0]
	v_pk_mul_f32 v[98:99], v[98:99], v[120:121] op_sel_hi:[1,0]
	s_cbranch_vccnz .LBB0_226
	v_lshlrev_b64 v[120:121], 12, v[116:117]
	v_lshl_add_u64 v[124:125], v[152:153], 0, v[120:121]
	v_cvt_pk_bf16_f32 v120, v110, v111
	v_cvt_pk_bf16_f32 v121, v112, v113
	v_cvt_pk_bf16_f32 v122, v106, v107
	v_cvt_pk_bf16_f32 v123, v108, v109
	s_mov_b64 s[42:43], 0
	global_store_dwordx4 v[124:125], v[120:123], off
	s_nop 1
	v_cvt_pk_bf16_f32 v120, v102, v103
	v_cvt_pk_bf16_f32 v121, v104, v105
	v_cvt_pk_bf16_f32 v122, v98, v99
	v_cvt_pk_bf16_f32 v123, v100, v101
	global_store_dwordx4 v[124:125], v[120:123], off offset:256
.LBB0_226:
	s_andn2_b64 vcc, exec, s[42:43]
	s_cbranch_vccnz .LBB0_228
	v_lshlrev_b32_e32 v126, 8, v118
	v_mov_b32_e32 v127, v139
	v_lshl_add_u64 v[122:123], v[142:143], 0, v[126:127]
	v_lshl_add_u64 v[238:239], v[238:239], 0, s[86:87]
	v_lshl_add_u64 v[240:241], v[240:241], 0, s[86:87]
	global_load_dwordx4 v[206:209], v[238:239], off
	global_load_dwordx4 v[210:213], v[238:239], off offset:16
	global_load_dwordx4 v[214:217], v[240:241], off
	global_load_dwordx4 v[218:221], v[240:241], off offset:16
	s_nop 0
	v_lshl_add_u64 v[154:155], v[140:141], 0, v[126:127]
	s_nop 0
	v_lshlrev_b64 v[116:117], 12, v[116:117]
	v_lshl_add_u64 v[116:117], v[114:115], 0, v[116:117]
	s_waitcnt vmcnt(9)
	v_pk_mul_f32 v[168:169], v[104:105], v[224:225]
	v_pk_mul_f32 v[170:171], v[102:103], v[222:223]
	s_waitcnt vmcnt(8)
	v_pk_mul_f32 v[172:173], v[100:101], v[228:229]
	v_pk_mul_f32 v[174:175], v[98:99], v[226:227]
	v_pk_mul_f32 v[224:225], v[112:113], v[224:225]
	v_pk_mul_f32 v[222:223], v[110:111], v[222:223]
	v_pk_mul_f32 v[228:229], v[108:109], v[228:229]
	v_pk_mul_f32 v[226:227], v[106:107], v[226:227]
	s_waitcnt vmcnt(7)
	v_pk_fma_f32 v[112:113], v[112:113], v[232:233], v[168:169] neg_lo:[0,0,1] neg_hi:[0,0,1]
	v_pk_fma_f32 v[110:111], v[110:111], v[230:231], v[170:171] neg_lo:[0,0,1] neg_hi:[0,0,1]
	s_waitcnt vmcnt(6)
	v_pk_fma_f32 v[108:109], v[108:109], v[236:237], v[172:173] neg_lo:[0,0,1] neg_hi:[0,0,1]
	v_pk_fma_f32 v[106:107], v[106:107], v[234:235], v[174:175] neg_lo:[0,0,1] neg_hi:[0,0,1]
	v_pk_fma_f32 v[104:105], v[104:105], v[232:233], v[224:225]
	v_pk_fma_f32 v[102:103], v[102:103], v[230:231], v[222:223]
	v_pk_fma_f32 v[222:223], v[100:101], v[236:237], v[228:229]
	v_pk_fma_f32 v[224:225], v[98:99], v[234:235], v[226:227]
	v_cvt_pk_bf16_f32 v98, v110, v111
	v_cvt_pk_bf16_f32 v99, v112, v113
	v_cvt_pk_bf16_f32 v100, v106, v107
	v_cvt_pk_bf16_f32 v101, v108, v109
	v_cvt_pk_bf16_f32 v102, v102, v103
	v_cvt_pk_bf16_f32 v103, v104, v105
	s_nop 0
	v_cvt_pk_bf16_f32 v104, v224, v225
	v_cvt_pk_bf16_f32 v105, v222, v223
	global_store_dwordx4 v[116:117], v[98:101], off
	global_store_dwordx4 v[116:117], v[102:105], off offset:128
.LBB0_228:
	s_nop 0
	v_or_b32_e32 v98, s17, v165
	v_ashrrev_i32_e32 v99, 31, v98
	v_lshl_add_u64 v[100:101], v[98:99], 2, s[6:7]
	s_nop 0
	v_and_or_b32 v100, v98, s77, 16
	v_add_u32_e32 v98, s35, v100
	s_mov_b64 s[42:43], -1
	s_and_b64 vcc, exec, s[2:3]
	v_ashrrev_i32_e32 v99, 31, v98
	v_mov_b32_e32 v102, v248
	v_pk_mul_f32 v[96:97], v[96:97], v[102:103] op_sel_hi:[1,0]
	v_pk_mul_f32 v[94:95], v[94:95], v[102:103] op_sel_hi:[1,0]
	v_pk_mul_f32 v[92:93], v[92:93], v[102:103] op_sel_hi:[1,0]
	v_pk_mul_f32 v[90:91], v[90:91], v[102:103] op_sel_hi:[1,0]
	v_pk_mul_f32 v[88:89], v[88:89], v[102:103] op_sel_hi:[1,0]
	v_pk_mul_f32 v[86:87], v[86:87], v[102:103] op_sel_hi:[1,0]
	v_pk_mul_f32 v[84:85], v[84:85], v[102:103] op_sel_hi:[1,0]
	v_pk_mul_f32 v[82:83], v[82:83], v[102:103] op_sel_hi:[1,0]
	s_cbranch_vccnz .LBB0_230
	v_lshlrev_b64 v[102:103], 12, v[98:99]
	v_lshl_add_u64 v[106:107], v[152:153], 0, v[102:103]
	v_cvt_pk_bf16_f32 v102, v94, v95
	v_cvt_pk_bf16_f32 v103, v96, v97
	v_cvt_pk_bf16_f32 v104, v90, v91
	v_cvt_pk_bf16_f32 v105, v92, v93
	s_mov_b64 s[42:43], 0
	global_store_dwordx4 v[106:107], v[102:105], off
	s_nop 1
	v_cvt_pk_bf16_f32 v102, v86, v87
	v_cvt_pk_bf16_f32 v103, v88, v89
	v_cvt_pk_bf16_f32 v104, v82, v83
	v_cvt_pk_bf16_f32 v105, v84, v85
	global_store_dwordx4 v[106:107], v[102:105], off offset:256

; __device__ __forceinline__ u32x4 pack8f(const f32x4 a, const f32x4 b) { u32x4 w; w.x = cvt_pk_bf16(a[0], a[1]); w.y = cvt_pk_bf16(a[2], a[3]); w.z = cvt_pk_bf16(b[0], b[1]); w.w = cvt_pk_bf16(b[2], b[3]); return w; }
;     __device__ __forceinline__ void operator()(const f32x4 (&acc)[2][2][4][2], const Unit& u, int wr, int wc, int fr, int fq) const {
;     ...
;                 const int grow = u.pm * BM + ai * HALF + wr * 64 + m * 16 + fr;
;                 const int pos = NMETA_ + (grow & 4095), srow = (grow >> 12) * TPAD + pos;
;                 const float rr = rs1[grow];
;                 const f32x4 a00 = acc[ai][0][m][0] * rr, a01 = acc[ai][0][m][1] * rr, a10 = acc[ai][1][m][0] * rr, a11 = acc[ai][1][m][1] * rr;
;     ...
;                     for (int bj = 0; bj < 2; ++bj) { const u32x4 w = bj ? pack8f(a10, a11) : pack8f(a00, a01);
;                         bf16_t* p = buf + (size_t)srow * 2048 + hd * 256 + bj * HALF + j0;
;                         *(u32x4*)p = w; }
.LBB0_232:
	s_nop 0
	v_or_b32_e32 v82, s17, v166
	v_ashrrev_i32_e32 v83, 31, v82
	v_lshl_add_u64 v[82:83], v[82:83], 2, s[6:7]
	s_nop 0
	v_bitop3_b32 v82, s17, v167, v166 bitop3:0xc8
	v_add_u32_e32 v84, 16, v82
	v_add_u32_e32 v82, s35, v84
	s_mov_b64 s[42:43], -1
	s_and_b64 vcc, exec, s[2:3]
	v_ashrrev_i32_e32 v83, 31, v82
	v_mov_b32_e32 v86, v249
	v_pk_mul_f32 v[80:81], v[80:81], v[86:87] op_sel_hi:[1,0]
	v_pk_mul_f32 v[78:79], v[78:79], v[86:87] op_sel_hi:[1,0]
	v_pk_mul_f32 v[76:77], v[76:77], v[86:87] op_sel_hi:[1,0]
	v_pk_mul_f32 v[74:75], v[74:75], v[86:87] op_sel_hi:[1,0]
	v_pk_mul_f32 v[72:73], v[72:73], v[86:87] op_sel_hi:[1,0]
	v_pk_mul_f32 v[70:71], v[70:71], v[86:87] op_sel_hi:[1,0]
	v_pk_mul_f32 v[68:69], v[68:69], v[86:87] op_sel_hi:[1,0]
	v_pk_mul_f32 v[66:67], v[66:67], v[86:87] op_sel_hi:[1,0]
	s_cbranch_vccnz .LBB0_234
	v_lshlrev_b64 v[86:87], 12, v[82:83]
	v_lshl_add_u64 v[90:91], v[152:153], 0, v[86:87]
	v_cvt_pk_bf16_f32 v86, v78, v79
	v_cvt_pk_bf16_f32 v87, v80, v81
	v_cvt_pk_bf16_f32 v88, v74, v75
	v_cvt_pk_bf16_f32 v89, v76, v77
	s_mov_b64 s[42:43], 0
	global_store_dwordx4 v[90:91], v[86:89], off
	s_nop 1
	v_cvt_pk_bf16_f32 v86, v70, v71
	v_cvt_pk_bf16_f32 v87, v72, v73
	v_cvt_pk_bf16_f32 v88, v66, v67
	v_cvt_pk_bf16_f32 v89, v68, v69
	global_store_dwordx4 v[90:91], v[86:89], off offset:256

; __device__ __forceinline__ u32x4 pack8f(const f32x4 a, const f32x4 b) { u32x4 w; w.x = cvt_pk_bf16(a[0], a[1]); w.y = cvt_pk_bf16(a[2], a[3]); w.z = cvt_pk_bf16(b[0], b[1]); w.w = cvt_pk_bf16(b[2], b[3]); return w; }
;     __device__ __forceinline__ void operator()(const f32x4 (&acc)[2][2][4][2], const Unit& u, int wr, int wc, int fr, int fq) const {
;     ...
;                 const int grow = u.pm * BM + ai * HALF + wr * 64 + m * 16 + fr;
;                 const int pos = NMETA_ + (grow & 4095), srow = (grow >> 12) * TPAD + pos;
;                 const float rr = rs1[grow];
;                 const f32x4 a00 = acc[ai][0][m][0] * rr, a01 = acc[ai][0][m][1] * rr, a10 = acc[ai][1][m][0] * rr, a11 = acc[ai][1][m][1] * rr;
;     ...
;                     for (int bj = 0; bj < 2; ++bj) { const u32x4 w = bj ? pack8f(a10, a11) : pack8f(a00, a01);
;                         bf16_t* p = buf + (size_t)srow * 2048 + hd * 256 + bj * HALF + j0;
;                         *(u32x4*)p = w; }
.LBB0_236:
	s_addk_i32 s17, 0x80
	v_or_b32_e32 v66, s17, v158
	v_ashrrev_i32_e32 v67, 31, v66
	v_lshl_add_u64 v[68:69], v[66:67], 2, s[6:7]
	s_nop 0
	s_ashr_i32 s35, s17, 12
	v_and_or_b32 v68, v66, s76, 16
	s_mulk_i32 s35, 0x1080
	v_add_u32_e32 v66, s35, v68
	s_mov_b64 s[42:43], -1
	s_and_b64 vcc, exec, s[2:3]
	v_ashrrev_i32_e32 v67, 31, v66
	v_mov_b32_e32 v70, v250
	v_pk_mul_f32 v[64:65], v[64:65], v[70:71] op_sel_hi:[1,0]
	v_pk_mul_f32 v[62:63], v[62:63], v[70:71] op_sel_hi:[1,0]
	v_pk_mul_f32 v[60:61], v[60:61], v[70:71] op_sel_hi:[1,0]
	v_pk_mul_f32 v[58:59], v[58:59], v[70:71] op_sel_hi:[1,0]
	v_pk_mul_f32 v[56:57], v[56:57], v[70:71] op_sel_hi:[1,0]
	v_pk_mul_f32 v[54:55], v[54:55], v[70:71] op_sel_hi:[1,0]
	v_pk_mul_f32 v[52:53], v[52:53], v[70:71] op_sel_hi:[1,0]
	v_pk_mul_f32 v[50:51], v[50:51], v[70:71] op_sel_hi:[1,0]
	s_cbranch_vccnz .LBB0_238
	v_lshlrev_b64 v[70:71], 12, v[66:67]
	v_lshl_add_u64 v[74:75], v[152:153], 0, v[70:71]
	v_cvt_pk_bf16_f32 v70, v62, v63
	v_cvt_pk_bf16_f32 v71, v64, v65
	v_cvt_pk_bf16_f32 v72, v58, v59
	v_cvt_pk_bf16_f32 v73, v60, v61
	s_mov_b64 s[42:43], 0
	global_store_dwordx4 v[74:75], v[70:73], off
	s_nop 1
	v_cvt_pk_bf16_f32 v70, v54, v55
	v_cvt_pk_bf16_f32 v71, v56, v57
	v_cvt_pk_bf16_f32 v72, v50, v51
	v_cvt_pk_bf16_f32 v73, v52, v53
	global_store_dwordx4 v[74:75], v[70:73], off offset:256

; __device__ __forceinline__ u32x4 pack8f(const f32x4 a, const f32x4 b) { u32x4 w; w.x = cvt_pk_bf16(a[0], a[1]); w.y = cvt_pk_bf16(a[2], a[3]); w.z = cvt_pk_bf16(b[0], b[1]); w.w = cvt_pk_bf16(b[2], b[3]); return w; }
;     __device__ __forceinline__ void operator()(const f32x4 (&acc)[2][2][4][2], const Unit& u, int wr, int wc, int fr, int fq) const {
;     ...
;                 const int grow = u.pm * BM + ai * HALF + wr * 64 + m * 16 + fr;
;                 const int pos = NMETA_ + (grow & 4095), srow = (grow >> 12) * TPAD + pos;
;                 const float rr = rs1[grow];
;                 const f32x4 a00 = acc[ai][0][m][0] * rr, a01 = acc[ai][0][m][1] * rr, a10 = acc[ai][1][m][0] * rr, a11 = acc[ai][1][m][1] * rr;
;     ...
;                     for (int bj = 0; bj < 2; ++bj) { const u32x4 w = bj ? pack8f(a10, a11) : pack8f(a00, a01);
;                         bf16_t* p = buf + (size_t)srow * 2048 + hd * 256 + bj * HALF + j0;
;                         *(u32x4*)p = w; }
.LBB0_240:
	s_nop 0
	v_or_b32_e32 v50, s17, v163
	v_ashrrev_i32_e32 v51, 31, v50
	v_lshl_add_u64 v[50:51], v[50:51], 2, s[6:7]
	s_nop 0
	v_bitop3_b32 v50, s17, v162, v163 bitop3:0xc8
	v_add_u32_e32 v52, 16, v50
	v_add_u32_e32 v50, s35, v52
	s_mov_b64 s[42:43], -1
	s_and_b64 vcc, exec, s[2:3]
	v_ashrrev_i32_e32 v51, 31, v50
	v_mov_b32_e32 v54, v251
	v_pk_mul_f32 v[48:49], v[48:49], v[54:55] op_sel_hi:[1,0]
	v_pk_mul_f32 v[46:47], v[46:47], v[54:55] op_sel_hi:[1,0]
	v_pk_mul_f32 v[44:45], v[44:45], v[54:55] op_sel_hi:[1,0]
	v_pk_mul_f32 v[42:43], v[42:43], v[54:55] op_sel_hi:[1,0]
	v_pk_mul_f32 v[40:41], v[40:41], v[54:55] op_sel_hi:[1,0]
	v_pk_mul_f32 v[38:39], v[38:39], v[54:55] op_sel_hi:[1,0]
	v_pk_mul_f32 v[36:37], v[36:37], v[54:55] op_sel_hi:[1,0]
	v_pk_mul_f32 v[34:35], v[34:35], v[54:55] op_sel_hi:[1,0]
	s_cbranch_vccnz .LBB0_242
	v_lshlrev_b64 v[54:55], 12, v[50:51]
	v_lshl_add_u64 v[58:59], v[152:153], 0, v[54:55]
	v_cvt_pk_bf16_f32 v54, v46, v47
	v_cvt_pk_bf16_f32 v55, v48, v49
	v_cvt_pk_bf16_f32 v56, v42, v43
	v_cvt_pk_bf16_f32 v57, v44, v45
	s_mov_b64 s[42:43], 0
	global_store_dwordx4 v[58:59], v[54:57], off
	s_nop 1
	v_cvt_pk_bf16_f32 v54, v38, v39
	v_cvt_pk_bf16_f32 v55, v40, v41
	v_cvt_pk_bf16_f32 v56, v34, v35
	v_cvt_pk_bf16_f32 v57, v36, v37
	global_store_dwordx4 v[58:59], v[54:57], off offset:256

; __device__ __forceinline__ u32x4 pack8f(const f32x4 a, const f32x4 b) { u32x4 w; w.x = cvt_pk_bf16(a[0], a[1]); w.y = cvt_pk_bf16(a[2], a[3]); w.z = cvt_pk_bf16(b[0], b[1]); w.w = cvt_pk_bf16(b[2], b[3]); return w; }
;     __device__ __forceinline__ void operator()(const f32x4 (&acc)[2][2][4][2], const Unit& u, int wr, int wc, int fr, int fq) const {
;     ...
;                 const int grow = u.pm * BM + ai * HALF + wr * 64 + m * 16 + fr;
;                 const int pos = NMETA_ + (grow & 4095), srow = (grow >> 12) * TPAD + pos;
;                 const float rr = rs1[grow];
;                 const f32x4 a00 = acc[ai][0][m][0] * rr, a01 = acc[ai][0][m][1] * rr, a10 = acc[ai][1][m][0] * rr, a11 = acc[ai][1][m][1] * rr;
;     ...
;                     for (int bj = 0; bj < 2; ++bj) { const u32x4 w = bj ? pack8f(a10, a11) : pack8f(a00, a01);
;                         bf16_t* p = buf + (size_t)srow * 2048 + hd * 256 + bj * HALF + j0;
;                         *(u32x4*)p = w; }
.LBB0_244:
	s_nop 0
	v_or_b32_e32 v34, s17, v165
	v_ashrrev_i32_e32 v35, 31, v34
	v_lshl_add_u64 v[36:37], v[34:35], 2, s[6:7]
	s_nop 0
	v_and_or_b32 v36, v34, s77, 16
	v_add_u32_e32 v34, s35, v36
	s_mov_b64 s[42:43], -1
	s_and_b64 vcc, exec, s[2:3]
	v_ashrrev_i32_e32 v35, 31, v34
	v_mov_b32_e32 v38, v252
	v_pk_mul_f32 v[32:33], v[32:33], v[38:39] op_sel_hi:[1,0]
	v_pk_mul_f32 v[30:31], v[30:31], v[38:39] op_sel_hi:[1,0]
	v_pk_mul_f32 v[28:29], v[28:29], v[38:39] op_sel_hi:[1,0]
	v_pk_mul_f32 v[26:27], v[26:27], v[38:39] op_sel_hi:[1,0]
	v_pk_mul_f32 v[24:25], v[24:25], v[38:39] op_sel_hi:[1,0]
	v_pk_mul_f32 v[22:23], v[22:23], v[38:39] op_sel_hi:[1,0]
	v_pk_mul_f32 v[20:21], v[20:21], v[38:39] op_sel_hi:[1,0]
	v_pk_mul_f32 v[18:19], v[18:19], v[38:39] op_sel_hi:[1,0]
	s_cbranch_vccnz .LBB0_246
	v_lshlrev_b64 v[38:39], 12, v[34:35]
	v_lshl_add_u64 v[42:43], v[152:153], 0, v[38:39]
	v_cvt_pk_bf16_f32 v38, v30, v31
	v_cvt_pk_bf16_f32 v39, v32, v33
	v_cvt_pk_bf16_f32 v40, v26, v27
	v_cvt_pk_bf16_f32 v41, v28, v29
	s_mov_b64 s[42:43], 0
	global_store_dwordx4 v[42:43], v[38:41], off
	s_nop 1
	v_cvt_pk_bf16_f32 v38, v22, v23
	v_cvt_pk_bf16_f32 v39, v24, v25
	v_cvt_pk_bf16_f32 v40, v18, v19
	v_cvt_pk_bf16_f32 v41, v20, v21
	global_store_dwordx4 v[42:43], v[38:41], off offset:256

; __device__ __forceinline__ u32x4 pack8f(const f32x4 a, const f32x4 b) { u32x4 w; w.x = cvt_pk_bf16(a[0], a[1]); w.y = cvt_pk_bf16(a[2], a[3]); w.z = cvt_pk_bf16(b[0], b[1]); w.w = cvt_pk_bf16(b[2], b[3]); return w; }
;     __device__ __forceinline__ void operator()(const f32x4 (&acc)[2][2][4][2], const Unit& u, int wr, int wc, int fr, int fq) const {
;     ...
;                 const int grow = u.pm * BM + ai * HALF + wr * 64 + m * 16 + fr;
;                 const int pos = NMETA_ + (grow & 4095), srow = (grow >> 12) * TPAD + pos;
;                 const float rr = rs1[grow];
;                 const f32x4 a00 = acc[ai][0][m][0] * rr, a01 = acc[ai][0][m][1] * rr, a10 = acc[ai][1][m][0] * rr, a11 = acc[ai][1][m][1] * rr;
;     ...
;                     for (int bj = 0; bj < 2; ++bj) { const u32x4 w = bj ? pack8f(a10, a11) : pack8f(a00, a01);
;                         bf16_t* p = buf + (size_t)srow * 2048 + hd * 256 + bj * HALF + j0;
;                         *(u32x4*)p = w; }
.LBB0_248:
	s_nop 0
	v_or_b32_e32 v18, s17, v166
	v_ashrrev_i32_e32 v19, 31, v18
	v_lshl_add_u64 v[18:19], v[18:19], 2, s[6:7]
	s_nop 0
	v_bitop3_b32 v18, s17, v167, v166 bitop3:0xc8
	v_add_u32_e32 v20, 16, v18
	v_add_u32_e32 v18, s35, v20
	s_mov_b64 s[42:43], -1
	s_and_b64 vcc, exec, s[2:3]
	v_ashrrev_i32_e32 v19, 31, v18
	v_mov_b32_e32 v22, v253
	v_pk_mul_f32 v[16:17], v[16:17], v[22:23] op_sel_hi:[1,0]
	v_pk_mul_f32 v[14:15], v[14:15], v[22:23] op_sel_hi:[1,0]
	v_pk_mul_f32 v[12:13], v[12:13], v[22:23] op_sel_hi:[1,0]
	v_pk_mul_f32 v[10:11], v[10:11], v[22:23] op_sel_hi:[1,0]
	v_pk_mul_f32 v[8:9], v[8:9], v[22:23] op_sel_hi:[1,0]
	v_pk_mul_f32 v[6:7], v[6:7], v[22:23] op_sel_hi:[1,0]
	v_pk_mul_f32 v[4:5], v[4:5], v[22:23] op_sel_hi:[1,0]
	v_pk_mul_f32 v[2:3], v[2:3], v[22:23] op_sel_hi:[1,0]
	s_cbranch_vccz .LBB0_251
	s_andn2_b64 vcc, exec, s[42:43]
	s_cbranch_vccz .LBB0_252

; __device__ __forceinline__ float bf_lo(unsigned w) { return __uint_as_float(w << 16); }
; __device__ __forceinline__ float bf_hi(unsigned w) { return __uint_as_float(w & 0xffff0000u); }
; #define LRU_LOADX(it_) do { const int hd_ = (it_) & 15, bc_ = (it_) >> 4, c_ = bc_ % NCH, b_ = bc_ / NCH; _Pragma("unroll") for (int k = 0; k < 5; ++k) { const int pos = c_ * 64 + 2 * rg - 3 + k; \
;             xw[k] = (u32x4){0u, 0u, 0u, 0u}; if (pos >= 0) xw[k] = *(const u32x4*)(XRb + ((size_t)(b_ * TPAD + pos)) * 2048 + hd_ * 128 + chg * 8); } } while (0)
; __global__ void __launch_bounds__(512, 2) fwd_mega(Params P_by_kernarg) {
;     ...
;         for (int item = vcu; item < 2 * NCH * 16; item += G) {
;             const int hd = item & 15, bc = item >> 4, c64 = bc % NCH, b = bc / NCH, t0 = c64 * 64;
;             if (hd != loaded_hd) {
;                 __syncthreads();
;                 for (int i = tid; i < 1024; i += 512) { const int k = i >> 7, j = i & 127; float v;
;                     if (k < 4) v = KA->in[9][k * 2048 + hd * 128 + j]; else if (k == 4) v = KA->in[10][hd * 128 + j]; else if (k == 5) v = KA->in[12][hd * 128 + j]; else if (k == 6) v = KA->in[14][hd * 128 + j]; else v = spl[hd * 128 + j];
;                     PAR[i] = v; }
;                 const bf16_t* wrp = WTr + ((size_t)(hd * 128 + jt * 32 + l31)) * 128 + hi * 8; const bf16_t* wip = WTi + ((size_t)(hd * 128 + jt * 32 + l31)) * 128 + hi * 8;
; #pragma unroll
;                 for (int kk = 0; kk < 8; ++kk) { wrf[kk] = *(const bf16x8*)(wrp + kk * 16); wif[kk] = *(const bf16x8*)(wip + kk * 16); }
;                 loaded_hd = hd;
;                 __syncthreads();
;             }
;             { float xin[5][8];
; #pragma unroll
;               for (int k = 0; k < 5; ++k) { const u32x4 w = xw[k];
;                   xin[k][0] = bf_lo(w.x); xin[k][1] = bf_hi(w.x); xin[k][2] = bf_lo(w.y); xin[k][3] = bf_hi(w.y); xin[k][4] = bf_lo(w.z); xin[k][5] = bf_hi(w.z); xin[k][6] = bf_lo(w.w); xin[k][7] = bf_hi(w.w); }
;               if (item + G < 2 * NCH * 16) LRU_LOADX(item + G);
.LBB0_356:
	s_or_b64 exec, exec, s[46:47]
	v_add_u32_e32 v34, s16, v151
	v_lshlrev_b64 v[24:25], 8, v[34:35]
	v_lshl_add_u64 v[26:27], v[122:123], 0, v[24:25]
	v_lshl_add_u64 v[24:25], v[124:125], 0, v[24:25]
	global_load_dwordx4 v[46:49], v[26:27], off
	global_load_dwordx4 v[54:57], v[26:27], off offset:32
	global_load_dwordx4 v[38:41], v[24:25], off
	global_load_dwordx4 v[42:45], v[24:25], off offset:32
	global_load_dwordx4 v[62:65], v[26:27], off offset:64
	global_load_dwordx4 v[70:73], v[26:27], off offset:96
	global_load_dwordx4 v[50:53], v[24:25], off offset:64
	global_load_dwordx4 v[58:61], v[24:25], off offset:96
	global_load_dwordx4 v[78:81], v[26:27], off offset:128
	global_load_dwordx4 v[86:89], v[26:27], off offset:160
	global_load_dwordx4 v[66:69], v[24:25], off offset:128
	global_load_dwordx4 v[74:77], v[24:25], off offset:160
	global_load_dwordx4 v[94:97], v[26:27], off offset:192
	global_load_dwordx4 v[98:101], v[26:27], off offset:224
	global_load_dwordx4 v[82:85], v[24:25], off offset:192
	global_load_dwordx4 v[90:93], v[24:25], off offset:224
	s_mov_b32 s50, s57
	s_waitcnt lgkmcnt(0)
	s_barrier
	s_waitcnt vmcnt(0)
.LBB0_357:
	s_add_i32 s51, s56, s22
	s_cmpk_gt_i32 s51, 0x81f
	s_cselect_b64 s[6:7], -1, 0
	v_mov_b64_e32 v[120:121], v[16:17]
	v_mov_b64_e32 v[112:113], v[4:5]
	v_mov_b64_e32 v[104:105], v[12:13]
	v_mov_b64_e32 v[108:109], v[8:9]
	s_and_b64 vcc, exec, s[6:7]
	v_mov_b32_e32 v117, v18
	v_mov_b32_e32 v116, v22
	v_mov_b32_e32 v115, v21
	v_mov_b32_e32 v114, v20
	v_mov_b64_e32 v[118:119], v[14:15]
	v_mov_b64_e32 v[110:111], v[2:3]
	v_mov_b64_e32 v[102:103], v[10:11]
	v_mov_b64_e32 v[106:107], v[6:7]
	s_cbranch_vccnz .LBB0_369
	s_ashr_i32 s16, s51, 4
	s_mul_hi_i32 s46, s16, 0x7e07e07f
	s_lshr_b32 s47, s46, 31
	s_ashr_i32 s46, s46, 5
	s_add_i32 s48, s46, s47
	s_mul_i32 s46, s48, 0x41
	s_sub_i32 s16, s16, s46
	s_lshl_b32 s49, s16, 6
	s_lshl_b32 s16, s51, 8
	v_mov_b32_e32 v104, v35
	v_mov_b32_e32 v105, v35
	v_add_u32_e32 v19, s49, v150
	s_and_b32 s16, s16, 0xf00
	v_mov_b32_e32 v102, v35
	v_mov_b32_e32 v103, v35
	v_mov_b64_e32 v[108:109], v[104:105]
	s_mulk_i32 s48, 0x1080
	v_lshl_add_u64 v[24:25], v[126:127], 0, s[16:17]
	v_cmp_lt_i32_e32 vcc, -1, v19
	v_mov_b64_e32 v[106:107], v[102:103]
	s_and_saveexec_b64 s[46:47], vcc
	s_cbranch_execz .LBB0_360
	v_add_u32_e32 v26, s48, v19
	v_ashrrev_i32_e32 v27, 31, v26
	v_lshlrev_b64 v[26:27], 12, v[26:27]
	v_lshl_add_u64 v[26:27], v[24:25], 0, v[26:27]
	global_load_dwordx4 v[106:109], v[26:27], off

; __global__ void __launch_bounds__(512, 2) fwd_mega(Params P_by_kernarg) {
	.amdhsa_kernel _Z8fwd_mega6Params
		.amdhsa_group_segment_fixed_size 0
		.amdhsa_private_segment_fixed_size 0
		.amdhsa_kernarg_size 464
		.amdhsa_user_sgpr_count 2
		.amdhsa_user_sgpr_dispatch_ptr 0
		.amdhsa_user_sgpr_queue_ptr 0
		.amdhsa_user_sgpr_kernarg_segment_ptr 1
		.amdhsa_user_sgpr_dispatch_id 0
		.amdhsa_user_sgpr_kernarg_preload_length 0
		.amdhsa_user_sgpr_kernarg_preload_offset 0
		.amdhsa_user_sgpr_private_segment_size 0
		.amdhsa_uses_dynamic_stack 0
		.amdhsa_enable_private_segment 0
		.amdhsa_system_sgpr_workgroup_id_x 1
		.amdhsa_system_sgpr_workgroup_id_y 0
		.amdhsa_system_sgpr_workgroup_id_z 0
		.amdhsa_system_sgpr_workgroup_info 0
		.amdhsa_system_vgpr_workitem_id 2
		.amdhsa_next_free_vgpr 256
		.amdhsa_next_free_sgpr 90
		.amdhsa_accum_offset 256
		.amdhsa_reserve_vcc 1
		.amdhsa_float_round_mode_32 0
		.amdhsa_float_round_mode_16_64 0
		.amdhsa_float_denorm_mode_32 3
		.amdhsa_float_denorm_mode_16_64 3
		.amdhsa_dx10_clamp 1
		.amdhsa_ieee_mode 1
		.amdhsa_fp16_overflow 0
		.amdhsa_tg_split 0
		.amdhsa_exception_fp_ieee_invalid_op 0
		.amdhsa_exception_fp_denorm_src 0
		.amdhsa_exception_fp_ieee_div_zero 0
		.amdhsa_exception_fp_ieee_overflow 0
		.amdhsa_exception_fp_ieee_underflow 0
		.amdhsa_exception_fp_ieee_inexact 0
		.amdhsa_exception_int_div_zero 0
	.end_amdhsa_kernel

; __global__ void __launch_bounds__(512, 2) fwd_mega(Params P_by_kernarg) {
amdhsa.kernels:
  - .agpr_count:     0
    .args:
      - .offset:         0
        .size:           208
        .value_kind:     by_value
      - .offset:         208
        .size:           4
        .value_kind:     hidden_block_count_x
      - .offset:         212
        .size:           4
        .value_kind:     hidden_block_count_y
      - .offset:         216
        .size:           4
        .value_kind:     hidden_block_count_z
      - .offset:         220
        .size:           2
        .value_kind:     hidden_group_size_x
      - .offset:         222
        .size:           2
        .value_kind:     hidden_group_size_y
      - .offset:         224
        .size:           2
        .value_kind:     hidden_group_size_z
      - .offset:         226
        .size:           2
        .value_kind:     hidden_remainder_x
      - .offset:         228
        .size:           2
        .value_kind:     hidden_remainder_y
      - .offset:         230
        .size:           2
        .value_kind:     hidden_remainder_z
      - .offset:         248
        .size:           8
        .value_kind:     hidden_global_offset_x
      - .offset:         256
        .size:           8
        .value_kind:     hidden_global_offset_y
      - .offset:         264
        .size:           8
        .value_kind:     hidden_global_offset_z
      - .offset:         272
        .size:           2
        .value_kind:     hidden_grid_dims
      - .offset:         296
        .size:           8
        .value_kind:     hidden_multigrid_sync_arg
      - .offset:         328
        .size:           4
        .value_kind:     hidden_dynamic_lds_size
    .group_segment_fixed_size: 0
    .kernarg_segment_align: 8
    .kernarg_segment_size: 464
    .language:       OpenCL C
    .language_version:
      - 2
      - 0
    .max_flat_workgroup_size: 512
    .name:           _Z8fwd_mega6Params
    .private_segment_fixed_size: 0
    .sgpr_count:     96
    .sgpr_spill_count: 0
    .symbol:         _Z8fwd_mega6Params.kd
    .uniform_work_group_size: 1
    .uses_dynamic_stack: false
    .vgpr_count:     256
    .vgpr_spill_count: 0
    .wavefront_size: 64
